# GEMM MFMA clusters in snake order: every consecutive MFMA shares one operand fragment with its predecessor
# baseline (speedup 1.0000x reference)
.LBB0_238:
	v_add_u32_e32 v142, s85, v180
	v_add_u32_e32 v158, s86, v180
	ds_read_b128 v[130:133], v142
	ds_read_b128 v[134:137], v142 offset:1024
	ds_read_b128 v[138:141], v142 offset:2048
	ds_read_b128 v[142:145], v142 offset:3072
	ds_read_b128 v[146:149], v158
	ds_read_b128 v[172:175], v158 offset:1024
	ds_read_b128 v[176:179], v158 offset:2048
	ds_read_b128 v[210:213], v158 offset:3072
	s_add_u32 s60, s6, 0xfffc0080
	s_addc_u32 s61, s7, -1
	s_cmp_eq_u32 s96, 12
	s_cselect_b32 s69, s9, s61
	s_cselect_b32 s68, s45, s60
	s_cselect_b32 s67, s43, s95
	s_cselect_b32 s66, s93, s94
	v_lshl_add_u64 v[246:247], s[6:7], 0, v[164:165]
	s_add_i32 m0, s41, 0xc000
	ds_read_b128 v[214:217], v204
	ds_read_b128 v[218:221], v204 offset:1024
	ds_read_b128 v[222:225], v204 offset:2048
	ds_read_b128 v[226:229], v204 offset:3072
	ds_read_b128 v[230:233], v204 offset:4096
	ds_read_b128 v[234:237], v204 offset:5120
	ds_read_b128 v[238:241], v204 offset:6144
	ds_read_b128 v[242:245], v204 offset:7168
	global_load_lds_dwordx4 v[246:247], off
	v_lshl_add_u64 v[246:247], s[6:7], 0, v[166:167]
	s_add_i32 m0, s41, 0xe000
	s_nop 0
	global_load_lds_dwordx4 v[246:247], off
	s_waitcnt vmcnt(8)
	s_waitcnt lgkmcnt(0)
	s_barrier
	s_waitcnt lgkmcnt(0)
	v_mfma_f32_16x16x32_bf16 v[126:129], v[130:133], v[214:217], v[126:129]
	v_mfma_f32_16x16x32_bf16 v[122:125], v[138:141], v[214:217], v[122:125]
	v_mfma_f32_16x16x32_bf16 v[110:113], v[138:141], v[222:225], v[110:113]
	v_mfma_f32_16x16x32_bf16 v[118:121], v[130:133], v[222:225], v[118:121]
	v_mfma_f32_16x16x32_bf16 v[102:105], v[130:133], v[230:233], v[102:105]
	v_mfma_f32_16x16x32_bf16 v[94:97], v[138:141], v[230:233], v[94:97]
	v_mfma_f32_16x16x32_bf16 v[78:81], v[138:141], v[238:241], v[78:81]
	v_mfma_f32_16x16x32_bf16 v[86:89], v[130:133], v[238:241], v[86:89]
	v_mfma_f32_16x16x32_bf16 v[126:129], v[134:137], v[218:221], v[126:129]
	v_mfma_f32_16x16x32_bf16 v[122:125], v[142:145], v[218:221], v[122:125]
	v_mfma_f32_16x16x32_bf16 v[110:113], v[142:145], v[226:229], v[110:113]
	v_mfma_f32_16x16x32_bf16 v[118:121], v[134:137], v[226:229], v[118:121]
	v_mfma_f32_16x16x32_bf16 v[102:105], v[134:137], v[234:237], v[102:105]
	v_mfma_f32_16x16x32_bf16 v[94:97], v[142:145], v[234:237], v[94:97]
	v_mfma_f32_16x16x32_bf16 v[78:81], v[142:145], v[242:245], v[78:81]
	v_mfma_f32_16x16x32_bf16 v[86:89], v[134:137], v[242:245], v[86:89]
	v_mfma_f32_16x16x32_bf16 v[114:117], v[146:149], v[214:217], v[114:117]
	v_mfma_f32_16x16x32_bf16 v[106:109], v[176:179], v[214:217], v[106:109]
	v_mfma_f32_16x16x32_bf16 v[90:93], v[176:179], v[222:225], v[90:93]
	v_mfma_f32_16x16x32_bf16 v[98:101], v[146:149], v[222:225], v[98:101]
	v_mfma_f32_16x16x32_bf16 v[82:85], v[146:149], v[230:233], v[82:85]
	v_mfma_f32_16x16x32_bf16 v[74:77], v[176:179], v[230:233], v[74:77]
	v_mfma_f32_16x16x32_bf16 v[66:69], v[176:179], v[238:241], v[66:69]
	v_mfma_f32_16x16x32_bf16 v[70:73], v[146:149], v[238:241], v[70:73]
	v_mfma_f32_16x16x32_bf16 v[114:117], v[172:175], v[218:221], v[114:117]
	v_mfma_f32_16x16x32_bf16 v[106:109], v[210:213], v[218:221], v[106:109]
	v_mfma_f32_16x16x32_bf16 v[90:93], v[210:213], v[226:229], v[90:93]
	v_mfma_f32_16x16x32_bf16 v[98:101], v[172:175], v[226:229], v[98:101]
	v_mfma_f32_16x16x32_bf16 v[82:85], v[172:175], v[234:237], v[82:85]
	v_mfma_f32_16x16x32_bf16 v[74:77], v[210:213], v[234:237], v[74:77]
	v_mfma_f32_16x16x32_bf16 v[66:69], v[210:213], v[242:245], v[66:69]
	v_mfma_f32_16x16x32_bf16 v[70:73], v[172:175], v[242:245], v[70:73]
	s_barrier
	s_add_i32 s60, s85, s3
	v_lshl_add_u64 v[246:247], s[66:67], 0, v[152:153]
	s_mov_b32 m0, s60
	ds_read_b128 v[214:217], v204 offset:16384
	ds_read_b128 v[218:221], v204 offset:17408
	ds_read_b128 v[222:225], v204 offset:18432
	ds_read_b128 v[226:229], v204 offset:19456
	ds_read_b128 v[230:233], v204 offset:20480
	ds_read_b128 v[234:237], v204 offset:21504
	ds_read_b128 v[238:241], v204 offset:22528
	ds_read_b128 v[242:245], v204 offset:23552
	global_load_lds_dwordx4 v[246:247], off
	s_add_i32 m0, s60, 0x2000
	s_add_u32 s60, s66, 0x40000
	v_lshl_add_u64 v[248:249], s[66:67], 0, v[156:157]
	s_addc_u32 s61, s67, 0
	s_add_i32 s97, s86, s3
	global_load_lds_dwordx4 v[248:249], off
	v_lshl_add_u64 v[250:251], s[60:61], 0, v[152:153]
	s_mov_b32 m0, s97
	v_lshl_add_u64 v[252:253], s[68:69], 0, v[154:155]
	global_load_lds_dwordx4 v[250:251], off
	v_lshl_add_u64 v[250:251], s[60:61], 0, v[156:157]
	s_add_i32 m0, s97, 0x2000
	s_nop 0
	global_load_lds_dwordx4 v[250:251], off
	v_lshl_add_u64 v[250:251], s[68:69], 0, v[150:151]
	s_mov_b32 m0, s41
	s_nop 0
	global_load_lds_dwordx4 v[250:251], off
	s_mov_b32 m0, s70
	s_nop 0
	global_load_lds_dwordx4 v[252:253], off
	s_waitcnt vmcnt(8)
	s_waitcnt lgkmcnt(0)
	s_barrier
	s_waitcnt lgkmcnt(0)
	v_mfma_f32_16x16x32_bf16 v[62:65], v[130:133], v[214:217], v[62:65]
	v_mfma_f32_16x16x32_bf16 v[58:61], v[138:141], v[214:217], v[58:61]
	v_mfma_f32_16x16x32_bf16 v[46:49], v[138:141], v[222:225], v[46:49]
	v_mfma_f32_16x16x32_bf16 v[54:57], v[130:133], v[222:225], v[54:57]
	v_mfma_f32_16x16x32_bf16 v[38:41], v[130:133], v[230:233], v[38:41]
	v_mfma_f32_16x16x32_bf16 v[30:33], v[138:141], v[230:233], v[30:33]
	v_mfma_f32_16x16x32_bf16 v[14:17], v[138:141], v[238:241], v[14:17]
	v_mfma_f32_16x16x32_bf16 v[22:25], v[130:133], v[238:241], v[22:25]
	v_mfma_f32_16x16x32_bf16 v[62:65], v[134:137], v[218:221], v[62:65]
	v_mfma_f32_16x16x32_bf16 v[58:61], v[142:145], v[218:221], v[58:61]
	v_mfma_f32_16x16x32_bf16 v[46:49], v[142:145], v[226:229], v[46:49]
	v_mfma_f32_16x16x32_bf16 v[54:57], v[134:137], v[226:229], v[54:57]
	v_mfma_f32_16x16x32_bf16 v[38:41], v[134:137], v[234:237], v[38:41]
	v_mfma_f32_16x16x32_bf16 v[30:33], v[142:145], v[234:237], v[30:33]
	v_mfma_f32_16x16x32_bf16 v[14:17], v[142:145], v[242:245], v[14:17]
	v_mfma_f32_16x16x32_bf16 v[22:25], v[134:137], v[242:245], v[22:25]
	v_mfma_f32_16x16x32_bf16 v[50:53], v[146:149], v[214:217], v[50:53]
	v_mfma_f32_16x16x32_bf16 v[42:45], v[176:179], v[214:217], v[42:45]
	v_mfma_f32_16x16x32_bf16 v[26:29], v[176:179], v[222:225], v[26:29]
	v_mfma_f32_16x16x32_bf16 v[34:37], v[146:149], v[222:225], v[34:37]
	v_mfma_f32_16x16x32_bf16 v[18:21], v[146:149], v[230:233], v[18:21]
	v_mfma_f32_16x16x32_bf16 v[10:13], v[176:179], v[230:233], v[10:13]
	v_mfma_f32_16x16x32_bf16 v[2:5], v[176:179], v[238:241], v[2:5]
	v_mfma_f32_16x16x32_bf16 v[6:9], v[146:149], v[238:241], v[6:9]
	v_mfma_f32_16x16x32_bf16 v[50:53], v[172:175], v[218:221], v[50:53]
	v_mfma_f32_16x16x32_bf16 v[42:45], v[210:213], v[218:221], v[42:45]
	v_mfma_f32_16x16x32_bf16 v[26:29], v[210:213], v[226:229], v[26:29]
	v_mfma_f32_16x16x32_bf16 v[34:37], v[172:175], v[226:229], v[34:37]
	v_mfma_f32_16x16x32_bf16 v[18:21], v[172:175], v[234:237], v[18:21]
	v_mfma_f32_16x16x32_bf16 v[10:13], v[210:213], v[234:237], v[10:13]
	v_mfma_f32_16x16x32_bf16 v[2:5], v[210:213], v[242:245], v[2:5]
	v_mfma_f32_16x16x32_bf16 v[6:9], v[172:175], v[242:245], v[6:9]
	s_barrier
	s_add_i32 s97, 0, 0x18000
	s_add_i32 vcc_lo, 0, 0x1c000
	v_add_u32_e32 v142, s97, v180
	v_add_u32_e32 v158, vcc_lo, v180
	ds_read_b128 v[130:133], v142
	ds_read_b128 v[134:137], v142 offset:1024
	ds_read_b128 v[138:141], v142 offset:2048
	ds_read_b128 v[142:145], v142 offset:3072
	ds_read_b128 v[146:149], v158
	ds_read_b128 v[172:175], v158 offset:1024
	ds_read_b128 v[176:179], v158 offset:2048
	ds_read_b128 v[210:213], v158 offset:3072
	s_add_u32 s60, s68, 0x40000
	s_addc_u32 s61, s69, 0
	s_mov_b32 m0, s71
	v_lshl_add_u64 v[170:171], s[60:61], 0, v[150:151]
	ds_read_b128 v[214:217], v204 offset:32768
	ds_read_b128 v[218:221], v204 offset:33792
	ds_read_b128 v[222:225], v204 offset:34816
	ds_read_b128 v[226:229], v204 offset:35840
	ds_read_b128 v[230:233], v204 offset:36864
	ds_read_b128 v[234:237], v204 offset:37888
	ds_read_b128 v[238:241], v204 offset:38912
	ds_read_b128 v[242:245], v204 offset:39936
	global_load_lds_dwordx4 v[170:171], off
	v_lshl_add_u64 v[170:171], s[60:61], 0, v[154:155]
	s_mov_b32 m0, s72
	s_nop 0
	global_load_lds_dwordx4 v[170:171], off
	s_waitcnt vmcnt(8)
	s_waitcnt lgkmcnt(0)
	s_barrier
	s_waitcnt lgkmcnt(0)
	v_mfma_f32_16x16x32_bf16 v[126:129], v[130:133], v[214:217], v[126:129]
	v_mfma_f32_16x16x32_bf16 v[122:125], v[138:141], v[214:217], v[122:125]
	v_mfma_f32_16x16x32_bf16 v[110:113], v[138:141], v[222:225], v[110:113]
	v_mfma_f32_16x16x32_bf16 v[118:121], v[130:133], v[222:225], v[118:121]
	v_mfma_f32_16x16x32_bf16 v[102:105], v[130:133], v[230:233], v[102:105]
	v_mfma_f32_16x16x32_bf16 v[94:97], v[138:141], v[230:233], v[94:97]
	v_mfma_f32_16x16x32_bf16 v[78:81], v[138:141], v[238:241], v[78:81]
	v_mfma_f32_16x16x32_bf16 v[86:89], v[130:133], v[238:241], v[86:89]
	v_mfma_f32_16x16x32_bf16 v[126:129], v[134:137], v[218:221], v[126:129]
	v_mfma_f32_16x16x32_bf16 v[122:125], v[142:145], v[218:221], v[122:125]
	v_mfma_f32_16x16x32_bf16 v[110:113], v[142:145], v[226:229], v[110:113]
	v_mfma_f32_16x16x32_bf16 v[118:121], v[134:137], v[226:229], v[118:121]
	v_mfma_f32_16x16x32_bf16 v[102:105], v[134:137], v[234:237], v[102:105]
	v_mfma_f32_16x16x32_bf16 v[94:97], v[142:145], v[234:237], v[94:97]
	v_mfma_f32_16x16x32_bf16 v[78:81], v[142:145], v[242:245], v[78:81]
	v_mfma_f32_16x16x32_bf16 v[86:89], v[134:137], v[242:245], v[86:89]
	v_mfma_f32_16x16x32_bf16 v[114:117], v[146:149], v[214:217], v[114:117]
	v_mfma_f32_16x16x32_bf16 v[106:109], v[176:179], v[214:217], v[106:109]
	v_mfma_f32_16x16x32_bf16 v[90:93], v[176:179], v[222:225], v[90:93]
	v_mfma_f32_16x16x32_bf16 v[98:101], v[146:149], v[222:225], v[98:101]
	v_mfma_f32_16x16x32_bf16 v[82:85], v[146:149], v[230:233], v[82:85]
	v_mfma_f32_16x16x32_bf16 v[74:77], v[176:179], v[230:233], v[74:77]
	v_mfma_f32_16x16x32_bf16 v[66:69], v[176:179], v[238:241], v[66:69]
	v_mfma_f32_16x16x32_bf16 v[70:73], v[146:149], v[238:241], v[70:73]
	v_mfma_f32_16x16x32_bf16 v[114:117], v[172:175], v[218:221], v[114:117]
	v_mfma_f32_16x16x32_bf16 v[106:109], v[210:213], v[218:221], v[106:109]
	v_mfma_f32_16x16x32_bf16 v[90:93], v[210:213], v[226:229], v[90:93]
	v_mfma_f32_16x16x32_bf16 v[98:101], v[172:175], v[226:229], v[98:101]
	v_mfma_f32_16x16x32_bf16 v[82:85], v[172:175], v[234:237], v[82:85]
	v_mfma_f32_16x16x32_bf16 v[74:77], v[210:213], v[234:237], v[74:77]
	v_mfma_f32_16x16x32_bf16 v[66:69], v[210:213], v[242:245], v[66:69]
	v_mfma_f32_16x16x32_bf16 v[70:73], v[172:175], v[242:245], v[70:73]
	s_barrier
	s_add_i32 s60, s97, s3
	v_lshl_add_u64 v[170:171], v[246:247], 0, s[28:29]
	s_mov_b32 m0, s60
	ds_read_b128 v[214:217], v204 offset:49152
	ds_read_b128 v[218:221], v204 offset:50176
	ds_read_b128 v[222:225], v204 offset:51200
	ds_read_b128 v[226:229], v204 offset:52224
	ds_read_b128 v[230:233], v204 offset:53248
	ds_read_b128 v[234:237], v204 offset:54272
	ds_read_b128 v[238:241], v204 offset:55296
	ds_read_b128 v[242:245], v204 offset:56320
	global_load_lds_dwordx4 v[170:171], off
	s_add_i32 m0, s60, 0x2000
	s_add_u32 s60, s66, 0x40080
	v_lshl_add_u64 v[170:171], v[248:249], 0, s[28:29]
	s_addc_u32 s61, s67, 0
	s_add_i32 s66, vcc_lo, s3
	global_load_lds_dwordx4 v[170:171], off
	v_lshl_add_u64 v[170:171], s[60:61], 0, v[152:153]
	s_mov_b32 m0, s66
	s_nop 0
	global_load_lds_dwordx4 v[170:171], off
	v_lshl_add_u64 v[170:171], s[60:61], 0, v[156:157]
	s_add_i32 m0, s66, 0x2000
	s_nop 0
	global_load_lds_dwordx4 v[170:171], off
	v_lshl_add_u64 v[170:171], v[250:251], 0, s[28:29]
	s_mov_b32 m0, s76
	s_nop 0
	global_load_lds_dwordx4 v[170:171], off
	v_lshl_add_u64 v[170:171], v[252:253], 0, s[28:29]
	s_mov_b32 m0, s77
	s_nop 0
	global_load_lds_dwordx4 v[170:171], off
	s_waitcnt vmcnt(8)
	s_waitcnt lgkmcnt(0)
	s_barrier
	s_waitcnt lgkmcnt(0)
	v_mfma_f32_16x16x32_bf16 v[62:65], v[130:133], v[214:217], v[62:65]
	v_mfma_f32_16x16x32_bf16 v[58:61], v[138:141], v[214:217], v[58:61]
	v_mfma_f32_16x16x32_bf16 v[46:49], v[138:141], v[222:225], v[46:49]
	v_mfma_f32_16x16x32_bf16 v[54:57], v[130:133], v[222:225], v[54:57]
	v_mfma_f32_16x16x32_bf16 v[38:41], v[130:133], v[230:233], v[38:41]
	v_mfma_f32_16x16x32_bf16 v[30:33], v[138:141], v[230:233], v[30:33]
	v_mfma_f32_16x16x32_bf16 v[14:17], v[138:141], v[238:241], v[14:17]
	v_mfma_f32_16x16x32_bf16 v[22:25], v[130:133], v[238:241], v[22:25]
	v_mfma_f32_16x16x32_bf16 v[62:65], v[134:137], v[218:221], v[62:65]
	v_mfma_f32_16x16x32_bf16 v[58:61], v[142:145], v[218:221], v[58:61]
	v_mfma_f32_16x16x32_bf16 v[46:49], v[142:145], v[226:229], v[46:49]
	v_mfma_f32_16x16x32_bf16 v[54:57], v[134:137], v[226:229], v[54:57]
	v_mfma_f32_16x16x32_bf16 v[38:41], v[134:137], v[234:237], v[38:41]
	v_mfma_f32_16x16x32_bf16 v[30:33], v[142:145], v[234:237], v[30:33]
	v_mfma_f32_16x16x32_bf16 v[14:17], v[142:145], v[242:245], v[14:17]
	v_mfma_f32_16x16x32_bf16 v[22:25], v[134:137], v[242:245], v[22:25]
	v_mfma_f32_16x16x32_bf16 v[50:53], v[146:149], v[214:217], v[50:53]
	v_mfma_f32_16x16x32_bf16 v[42:45], v[176:179], v[214:217], v[42:45]
	v_mfma_f32_16x16x32_bf16 v[26:29], v[176:179], v[222:225], v[26:29]
	v_mfma_f32_16x16x32_bf16 v[34:37], v[146:149], v[222:225], v[34:37]
	v_mfma_f32_16x16x32_bf16 v[18:21], v[146:149], v[230:233], v[18:21]
	v_mfma_f32_16x16x32_bf16 v[10:13], v[176:179], v[230:233], v[10:13]
	v_mfma_f32_16x16x32_bf16 v[2:5], v[176:179], v[238:241], v[2:5]
	v_mfma_f32_16x16x32_bf16 v[6:9], v[146:149], v[238:241], v[6:9]
	v_mfma_f32_16x16x32_bf16 v[50:53], v[172:175], v[218:221], v[50:53]
	v_mfma_f32_16x16x32_bf16 v[42:45], v[210:213], v[218:221], v[42:45]
	v_mfma_f32_16x16x32_bf16 v[26:29], v[210:213], v[226:229], v[26:29]
	v_mfma_f32_16x16x32_bf16 v[34:37], v[172:175], v[226:229], v[34:37]
	v_mfma_f32_16x16x32_bf16 v[18:21], v[172:175], v[234:237], v[18:21]
	v_mfma_f32_16x16x32_bf16 v[10:13], v[210:213], v[234:237], v[10:13]
	v_mfma_f32_16x16x32_bf16 v[2:5], v[210:213], v[242:245], v[2:5]
	v_mfma_f32_16x16x32_bf16 v[6:9], v[172:175], v[242:245], v[6:9]
	s_barrier
	s_add_i32 s96, s96, 2
	s_add_u32 s6, s6, 0x100
	s_addc_u32 s7, s7, 0
	s_add_u32 s94, s94, 0x100
	s_addc_u32 s95, s95, 0
	s_cmp_gt_u32 s96, 13
	s_cbranch_scc0 .LBB0_238
	s_and_b64 vcc, exec, s[30:31]
	s_cbranch_vccnz .LBB0_243
	s_cmp_lg_u32 s8, 5
	s_mov_b64 s[6:7], -1
	s_cbranch_scc1 .LBB0_244

.LBB0_493:
	ds_read_b128 v[74:77], v170
	ds_read_b128 v[78:81], v170 offset:1024
	ds_read_b128 v[154:157], v170 offset:2048
	ds_read_b128 v[158:161], v170 offset:3072
	ds_read_b128 v[162:165], v171
	ds_read_b128 v[174:177], v171 offset:1024
	ds_read_b128 v[178:181], v171 offset:2048
	ds_read_b128 v[182:185], v171 offset:3072
	s_add_u32 s42, s40, 0xfffc0080
	s_addc_u32 s43, s41, -1
	s_cmp_eq_u32 s83, 12
	s_cselect_b32 s45, s25, s43
	s_cselect_b32 s44, s39, s42
	s_cselect_b32 s43, s19, s82
	s_cselect_b32 s42, s80, s81
	v_lshl_add_u64 v[166:167], s[40:41], 0, v[146:147]
	s_add_i32 m0, s64, 0xc000
	ds_read_b128 v[186:189], v172
	ds_read_b128 v[190:193], v172 offset:1024
	ds_read_b128 v[194:197], v172 offset:2048
	ds_read_b128 v[198:201], v172 offset:3072
	ds_read_b128 v[202:205], v172 offset:4096
	ds_read_b128 v[206:209], v172 offset:5120
	ds_read_b128 v[210:213], v172 offset:6144
	ds_read_b128 v[214:217], v172 offset:7168
	global_load_lds_dwordx4 v[166:167], off
	v_lshl_add_u64 v[166:167], s[40:41], 0, v[148:149]
	s_add_i32 m0, s64, 0xe000
	s_nop 0
	global_load_lds_dwordx4 v[166:167], off
	s_waitcnt vmcnt(8)
	s_waitcnt lgkmcnt(0)
	s_barrier
	s_waitcnt lgkmcnt(0)
	v_mfma_f32_16x16x32_bf16 v[86:89], v[74:77], v[186:189], v[86:89]
	v_mfma_f32_16x16x32_bf16 v[82:85], v[154:157], v[186:189], v[82:85]
	v_mfma_f32_16x16x32_bf16 v[122:125], v[154:157], v[194:197], v[122:125]
	v_mfma_f32_16x16x32_bf16 v[126:129], v[74:77], v[194:197], v[126:129]
	v_mfma_f32_16x16x32_bf16 v[110:113], v[74:77], v[202:205], v[110:113]
	v_mfma_f32_16x16x32_bf16 v[106:109], v[154:157], v[202:205], v[106:109]
	v_mfma_f32_16x16x32_bf16 v[90:93], v[154:157], v[210:213], v[90:93]
	v_mfma_f32_16x16x32_bf16 v[94:97], v[74:77], v[210:213], v[94:97]
	v_mfma_f32_16x16x32_bf16 v[86:89], v[78:81], v[190:193], v[86:89]
	v_mfma_f32_16x16x32_bf16 v[82:85], v[158:161], v[190:193], v[82:85]
	v_mfma_f32_16x16x32_bf16 v[122:125], v[158:161], v[198:201], v[122:125]
	v_mfma_f32_16x16x32_bf16 v[126:129], v[78:81], v[198:201], v[126:129]
	v_mfma_f32_16x16x32_bf16 v[110:113], v[78:81], v[206:209], v[110:113]
	v_mfma_f32_16x16x32_bf16 v[106:109], v[158:161], v[206:209], v[106:109]
	v_mfma_f32_16x16x32_bf16 v[90:93], v[158:161], v[214:217], v[90:93]
	v_mfma_f32_16x16x32_bf16 v[94:97], v[78:81], v[214:217], v[94:97]
	v_mfma_f32_16x16x32_bf16 v[134:137], v[162:165], v[186:189], v[134:137]
	v_mfma_f32_16x16x32_bf16 v[130:133], v[178:181], v[186:189], v[130:133]
	v_mfma_f32_16x16x32_bf16 v[114:117], v[178:181], v[194:197], v[114:117]
	v_mfma_f32_16x16x32_bf16 v[118:121], v[162:165], v[194:197], v[118:121]
	v_mfma_f32_16x16x32_bf16 v[102:105], v[162:165], v[202:205], v[102:105]
	v_mfma_f32_16x16x32_bf16 v[98:101], v[178:181], v[202:205], v[98:101]
	v_mfma_f32_16x16x32_bf16 v[66:69], v[178:181], v[210:213], v[66:69]
	v_mfma_f32_16x16x32_bf16 v[70:73], v[162:165], v[210:213], v[70:73]
	v_mfma_f32_16x16x32_bf16 v[134:137], v[174:177], v[190:193], v[134:137]
	v_mfma_f32_16x16x32_bf16 v[130:133], v[182:185], v[190:193], v[130:133]
	v_mfma_f32_16x16x32_bf16 v[114:117], v[182:185], v[198:201], v[114:117]
	v_mfma_f32_16x16x32_bf16 v[118:121], v[174:177], v[198:201], v[118:121]
	v_mfma_f32_16x16x32_bf16 v[102:105], v[174:177], v[206:209], v[102:105]
	v_mfma_f32_16x16x32_bf16 v[98:101], v[182:185], v[206:209], v[98:101]
	v_mfma_f32_16x16x32_bf16 v[66:69], v[182:185], v[214:217], v[66:69]
	v_mfma_f32_16x16x32_bf16 v[70:73], v[174:177], v[214:217], v[70:73]
	s_barrier
	s_add_i32 s60, s77, s63
	v_lshl_add_u64 v[166:167], s[42:43], 0, v[140:141]
	s_mov_b32 m0, s60
	ds_read_b128 v[186:189], v172 offset:16384
	ds_read_b128 v[190:193], v172 offset:17408
	ds_read_b128 v[194:197], v172 offset:18432
	ds_read_b128 v[198:201], v172 offset:19456
	ds_read_b128 v[202:205], v172 offset:20480
	ds_read_b128 v[206:209], v172 offset:21504
	ds_read_b128 v[210:213], v172 offset:22528
	ds_read_b128 v[214:217], v172 offset:23552
	global_load_lds_dwordx4 v[166:167], off
	s_add_i32 m0, s60, 0x2000
	s_add_u32 s60, s42, 0x40000
	v_lshl_add_u64 v[218:219], s[42:43], 0, v[144:145]
	s_addc_u32 s61, s43, 0
	s_add_i32 s84, s78, s63
	global_load_lds_dwordx4 v[218:219], off
	v_lshl_add_u64 v[220:221], s[60:61], 0, v[140:141]
	s_mov_b32 m0, s84
	v_lshl_add_u64 v[222:223], s[44:45], 0, v[142:143]
	global_load_lds_dwordx4 v[220:221], off
	v_lshl_add_u64 v[220:221], s[60:61], 0, v[144:145]
	s_add_i32 m0, s84, 0x2000
	s_nop 0
	global_load_lds_dwordx4 v[220:221], off
	v_lshl_add_u64 v[220:221], s[44:45], 0, v[138:139]
	s_mov_b32 m0, s64
	s_nop 0
	global_load_lds_dwordx4 v[220:221], off
	s_mov_b32 m0, s65
	s_nop 0
	global_load_lds_dwordx4 v[222:223], off
	s_waitcnt vmcnt(8)
	s_waitcnt lgkmcnt(0)
	s_barrier
	s_waitcnt lgkmcnt(0)
	v_mfma_f32_16x16x32_bf16 v[62:65], v[74:77], v[186:189], v[62:65]
	v_mfma_f32_16x16x32_bf16 v[58:61], v[154:157], v[186:189], v[58:61]
	v_mfma_f32_16x16x32_bf16 v[42:45], v[154:157], v[194:197], v[42:45]
	v_mfma_f32_16x16x32_bf16 v[46:49], v[74:77], v[194:197], v[46:49]
	v_mfma_f32_16x16x32_bf16 v[30:33], v[74:77], v[202:205], v[30:33]
	v_mfma_f32_16x16x32_bf16 v[26:29], v[154:157], v[202:205], v[26:29]
	v_mfma_f32_16x16x32_bf16 v[10:13], v[154:157], v[210:213], v[10:13]
	v_mfma_f32_16x16x32_bf16 v[14:17], v[74:77], v[210:213], v[14:17]
	v_mfma_f32_16x16x32_bf16 v[62:65], v[78:81], v[190:193], v[62:65]
	v_mfma_f32_16x16x32_bf16 v[58:61], v[158:161], v[190:193], v[58:61]
	v_mfma_f32_16x16x32_bf16 v[42:45], v[158:161], v[198:201], v[42:45]
	v_mfma_f32_16x16x32_bf16 v[46:49], v[78:81], v[198:201], v[46:49]
	v_mfma_f32_16x16x32_bf16 v[30:33], v[78:81], v[206:209], v[30:33]
	v_mfma_f32_16x16x32_bf16 v[26:29], v[158:161], v[206:209], v[26:29]
	v_mfma_f32_16x16x32_bf16 v[10:13], v[158:161], v[214:217], v[10:13]
	v_mfma_f32_16x16x32_bf16 v[14:17], v[78:81], v[214:217], v[14:17]
	v_mfma_f32_16x16x32_bf16 v[54:57], v[162:165], v[186:189], v[54:57]
	v_mfma_f32_16x16x32_bf16 v[50:53], v[178:181], v[186:189], v[50:53]
	v_mfma_f32_16x16x32_bf16 v[34:37], v[178:181], v[194:197], v[34:37]
	v_mfma_f32_16x16x32_bf16 v[38:41], v[162:165], v[194:197], v[38:41]
	v_mfma_f32_16x16x32_bf16 v[22:25], v[162:165], v[202:205], v[22:25]
	v_mfma_f32_16x16x32_bf16 v[18:21], v[178:181], v[202:205], v[18:21]
	v_mfma_f32_16x16x32_bf16 v[2:5], v[178:181], v[210:213], v[2:5]
	v_mfma_f32_16x16x32_bf16 v[6:9], v[162:165], v[210:213], v[6:9]
	v_mfma_f32_16x16x32_bf16 v[54:57], v[174:177], v[190:193], v[54:57]
	v_mfma_f32_16x16x32_bf16 v[50:53], v[182:185], v[190:193], v[50:53]
	v_mfma_f32_16x16x32_bf16 v[34:37], v[182:185], v[198:201], v[34:37]
	v_mfma_f32_16x16x32_bf16 v[38:41], v[174:177], v[198:201], v[38:41]
	v_mfma_f32_16x16x32_bf16 v[22:25], v[174:177], v[206:209], v[22:25]
	v_mfma_f32_16x16x32_bf16 v[18:21], v[182:185], v[206:209], v[18:21]
	v_mfma_f32_16x16x32_bf16 v[2:5], v[182:185], v[214:217], v[2:5]
	v_mfma_f32_16x16x32_bf16 v[6:9], v[174:177], v[214:217], v[6:9]
	s_barrier
	s_add_i32 s60, 0, 0x18000
	s_add_i32 s61, 0, 0x1c000
	v_add_u32_e32 v158, s60, v168
	v_add_u32_e32 v182, s61, v168
	ds_read_b128 v[74:77], v158
	ds_read_b128 v[78:81], v158 offset:1024
	ds_read_b128 v[154:157], v158 offset:2048
	ds_read_b128 v[158:161], v158 offset:3072
	ds_read_b128 v[162:165], v182
	ds_read_b128 v[174:177], v182 offset:1024
	ds_read_b128 v[178:181], v182 offset:2048
	ds_read_b128 v[182:185], v182 offset:3072
	s_add_u32 s44, s44, 0x40000
	s_addc_u32 s45, s45, 0
	s_mov_b32 m0, s66
	v_lshl_add_u64 v[224:225], s[44:45], 0, v[138:139]
	ds_read_b128 v[186:189], v172 offset:32768
	ds_read_b128 v[190:193], v172 offset:33792
	ds_read_b128 v[194:197], v172 offset:34816
	ds_read_b128 v[198:201], v172 offset:35840
	ds_read_b128 v[202:205], v172 offset:36864
	ds_read_b128 v[206:209], v172 offset:37888
	ds_read_b128 v[210:213], v172 offset:38912
	ds_read_b128 v[214:217], v172 offset:39936
	global_load_lds_dwordx4 v[224:225], off
	v_lshl_add_u64 v[224:225], s[44:45], 0, v[142:143]
	s_mov_b32 m0, s67
	s_nop 0
	global_load_lds_dwordx4 v[224:225], off
	s_waitcnt vmcnt(8)
	s_waitcnt lgkmcnt(0)
	s_barrier
	s_waitcnt lgkmcnt(0)
	v_mfma_f32_16x16x32_bf16 v[86:89], v[74:77], v[186:189], v[86:89]
	v_mfma_f32_16x16x32_bf16 v[82:85], v[154:157], v[186:189], v[82:85]
	v_mfma_f32_16x16x32_bf16 v[122:125], v[154:157], v[194:197], v[122:125]
	v_mfma_f32_16x16x32_bf16 v[126:129], v[74:77], v[194:197], v[126:129]
	v_mfma_f32_16x16x32_bf16 v[110:113], v[74:77], v[202:205], v[110:113]
	v_mfma_f32_16x16x32_bf16 v[106:109], v[154:157], v[202:205], v[106:109]
	v_mfma_f32_16x16x32_bf16 v[90:93], v[154:157], v[210:213], v[90:93]
	v_mfma_f32_16x16x32_bf16 v[94:97], v[74:77], v[210:213], v[94:97]
	v_mfma_f32_16x16x32_bf16 v[86:89], v[78:81], v[190:193], v[86:89]
	v_mfma_f32_16x16x32_bf16 v[82:85], v[158:161], v[190:193], v[82:85]
	v_mfma_f32_16x16x32_bf16 v[122:125], v[158:161], v[198:201], v[122:125]
	v_mfma_f32_16x16x32_bf16 v[126:129], v[78:81], v[198:201], v[126:129]
	v_mfma_f32_16x16x32_bf16 v[110:113], v[78:81], v[206:209], v[110:113]
	v_mfma_f32_16x16x32_bf16 v[106:109], v[158:161], v[206:209], v[106:109]
	v_mfma_f32_16x16x32_bf16 v[90:93], v[158:161], v[214:217], v[90:93]
	v_mfma_f32_16x16x32_bf16 v[94:97], v[78:81], v[214:217], v[94:97]
	v_mfma_f32_16x16x32_bf16 v[134:137], v[162:165], v[186:189], v[134:137]
	v_mfma_f32_16x16x32_bf16 v[130:133], v[178:181], v[186:189], v[130:133]
	v_mfma_f32_16x16x32_bf16 v[114:117], v[178:181], v[194:197], v[114:117]
	v_mfma_f32_16x16x32_bf16 v[118:121], v[162:165], v[194:197], v[118:121]
	v_mfma_f32_16x16x32_bf16 v[102:105], v[162:165], v[202:205], v[102:105]
	v_mfma_f32_16x16x32_bf16 v[98:101], v[178:181], v[202:205], v[98:101]
	v_mfma_f32_16x16x32_bf16 v[66:69], v[178:181], v[210:213], v[66:69]
	v_mfma_f32_16x16x32_bf16 v[70:73], v[162:165], v[210:213], v[70:73]
	v_mfma_f32_16x16x32_bf16 v[134:137], v[174:177], v[190:193], v[134:137]
	v_mfma_f32_16x16x32_bf16 v[130:133], v[182:185], v[190:193], v[130:133]
	v_mfma_f32_16x16x32_bf16 v[114:117], v[182:185], v[198:201], v[114:117]
	v_mfma_f32_16x16x32_bf16 v[118:121], v[174:177], v[198:201], v[118:121]
	v_mfma_f32_16x16x32_bf16 v[102:105], v[174:177], v[206:209], v[102:105]
	v_mfma_f32_16x16x32_bf16 v[98:101], v[182:185], v[206:209], v[98:101]
	v_mfma_f32_16x16x32_bf16 v[66:69], v[182:185], v[214:217], v[66:69]
	v_mfma_f32_16x16x32_bf16 v[70:73], v[174:177], v[214:217], v[70:73]
	s_barrier
	s_add_i32 s44, s60, s63
	v_lshl_add_u64 v[166:167], v[166:167], 0, s[14:15]
	s_mov_b32 m0, s44
	ds_read_b128 v[186:189], v172 offset:49152
	ds_read_b128 v[190:193], v172 offset:50176
	ds_read_b128 v[194:197], v172 offset:51200
	ds_read_b128 v[198:201], v172 offset:52224
	ds_read_b128 v[202:205], v172 offset:53248
	ds_read_b128 v[206:209], v172 offset:54272
	ds_read_b128 v[210:213], v172 offset:55296
	ds_read_b128 v[214:217], v172 offset:56320
	global_load_lds_dwordx4 v[166:167], off
	s_add_i32 m0, s44, 0x2000
	s_add_u32 s42, s42, 0x40080
	v_lshl_add_u64 v[166:167], v[218:219], 0, s[14:15]
	s_addc_u32 s43, s43, 0
	s_add_i32 s44, s61, s63
	global_load_lds_dwordx4 v[166:167], off
	v_lshl_add_u64 v[166:167], s[42:43], 0, v[140:141]
	s_mov_b32 m0, s44
	s_nop 0
	global_load_lds_dwordx4 v[166:167], off
	v_lshl_add_u64 v[166:167], s[42:43], 0, v[144:145]
	s_add_i32 m0, s44, 0x2000
	s_nop 0
	global_load_lds_dwordx4 v[166:167], off
	v_lshl_add_u64 v[166:167], v[220:221], 0, s[14:15]
	s_mov_b32 m0, s74
	s_nop 0
	global_load_lds_dwordx4 v[166:167], off
	v_lshl_add_u64 v[166:167], v[222:223], 0, s[14:15]
	s_mov_b32 m0, s75
	s_nop 0
	global_load_lds_dwordx4 v[166:167], off
	s_waitcnt vmcnt(8)
	s_waitcnt lgkmcnt(0)
	s_barrier
	s_waitcnt lgkmcnt(0)
	v_mfma_f32_16x16x32_bf16 v[62:65], v[74:77], v[186:189], v[62:65]
	v_mfma_f32_16x16x32_bf16 v[58:61], v[154:157], v[186:189], v[58:61]
	v_mfma_f32_16x16x32_bf16 v[42:45], v[154:157], v[194:197], v[42:45]
	v_mfma_f32_16x16x32_bf16 v[46:49], v[74:77], v[194:197], v[46:49]
	v_mfma_f32_16x16x32_bf16 v[30:33], v[74:77], v[202:205], v[30:33]
	v_mfma_f32_16x16x32_bf16 v[26:29], v[154:157], v[202:205], v[26:29]
	v_mfma_f32_16x16x32_bf16 v[10:13], v[154:157], v[210:213], v[10:13]
	v_mfma_f32_16x16x32_bf16 v[14:17], v[74:77], v[210:213], v[14:17]
	v_mfma_f32_16x16x32_bf16 v[62:65], v[78:81], v[190:193], v[62:65]
	v_mfma_f32_16x16x32_bf16 v[58:61], v[158:161], v[190:193], v[58:61]
	v_mfma_f32_16x16x32_bf16 v[42:45], v[158:161], v[198:201], v[42:45]
	v_mfma_f32_16x16x32_bf16 v[46:49], v[78:81], v[198:201], v[46:49]
	v_mfma_f32_16x16x32_bf16 v[30:33], v[78:81], v[206:209], v[30:33]
	v_mfma_f32_16x16x32_bf16 v[26:29], v[158:161], v[206:209], v[26:29]
	v_mfma_f32_16x16x32_bf16 v[10:13], v[158:161], v[214:217], v[10:13]
	v_mfma_f32_16x16x32_bf16 v[14:17], v[78:81], v[214:217], v[14:17]
	v_mfma_f32_16x16x32_bf16 v[54:57], v[162:165], v[186:189], v[54:57]
	v_mfma_f32_16x16x32_bf16 v[50:53], v[178:181], v[186:189], v[50:53]
	v_mfma_f32_16x16x32_bf16 v[34:37], v[178:181], v[194:197], v[34:37]
	v_mfma_f32_16x16x32_bf16 v[38:41], v[162:165], v[194:197], v[38:41]
	v_mfma_f32_16x16x32_bf16 v[22:25], v[162:165], v[202:205], v[22:25]
	v_mfma_f32_16x16x32_bf16 v[18:21], v[178:181], v[202:205], v[18:21]
	v_mfma_f32_16x16x32_bf16 v[2:5], v[178:181], v[210:213], v[2:5]
	v_mfma_f32_16x16x32_bf16 v[6:9], v[162:165], v[210:213], v[6:9]
	v_mfma_f32_16x16x32_bf16 v[54:57], v[174:177], v[190:193], v[54:57]
	v_mfma_f32_16x16x32_bf16 v[50:53], v[182:185], v[190:193], v[50:53]
	v_mfma_f32_16x16x32_bf16 v[34:37], v[182:185], v[198:201], v[34:37]
	v_mfma_f32_16x16x32_bf16 v[38:41], v[174:177], v[198:201], v[38:41]
	v_mfma_f32_16x16x32_bf16 v[22:25], v[174:177], v[206:209], v[22:25]
	v_mfma_f32_16x16x32_bf16 v[18:21], v[182:185], v[206:209], v[18:21]
	v_mfma_f32_16x16x32_bf16 v[2:5], v[182:185], v[214:217], v[2:5]
	v_mfma_f32_16x16x32_bf16 v[6:9], v[174:177], v[214:217], v[6:9]
	s_barrier
	s_add_i32 s83, s83, 2
	s_add_u32 s40, s40, 0x100
	s_addc_u32 s41, s41, 0
	s_add_u32 s81, s81, 0x100
	s_addc_u32 s82, s82, 0
	s_cmp_gt_u32 s83, 13
	s_cbranch_scc0 .LBB0_493
	s_and_b64 vcc, exec, s[16:17]
	s_cbranch_vccz .LBB0_496
	s_barrier

.LBB0_584:
	ds_read_b128 v[130:133], v166
	ds_read_b128 v[134:137], v166 offset:1024
	ds_read_b128 v[138:141], v166 offset:2048
	ds_read_b128 v[142:145], v166 offset:3072
	ds_read_b128 v[170:173], v167
	ds_read_b128 v[174:177], v167 offset:1024
	ds_read_b128 v[178:181], v167 offset:2048
	ds_read_b128 v[182:185], v167 offset:3072
	s_add_u32 s36, s30, 0xfffc0080
	s_addc_u32 s37, s31, -1
	s_cmp_eq_u32 s75, 12
	s_cselect_b32 s39, s17, s37
	s_cselect_b32 s38, s71, s36
	s_cselect_b32 s37, s15, s74
	s_cselect_b32 s36, s72, s73
	v_lshl_add_u64 v[220:221], s[30:31], 0, v[154:155]
	s_add_i32 m0, s29, 0xc000
	ds_read_b128 v[186:189], v168
	ds_read_b128 v[190:193], v168 offset:1024
	ds_read_b128 v[194:197], v168 offset:2048
	ds_read_b128 v[198:201], v168 offset:3072
	ds_read_b128 v[202:205], v168 offset:4096
	ds_read_b128 v[206:209], v168 offset:5120
	ds_read_b128 v[212:215], v168 offset:6144
	ds_read_b128 v[216:219], v168 offset:7168
	global_load_lds_dwordx4 v[220:221], off
	v_lshl_add_u64 v[220:221], s[30:31], 0, v[156:157]
	s_add_i32 m0, s29, 0xe000
	s_nop 0
	global_load_lds_dwordx4 v[220:221], off
	s_waitcnt vmcnt(8)
	s_waitcnt lgkmcnt(0)
	s_barrier
	s_waitcnt lgkmcnt(0)
	v_mfma_f32_16x16x32_bf16 v[126:129], v[130:133], v[186:189], v[126:129]
	v_mfma_f32_16x16x32_bf16 v[122:125], v[138:141], v[186:189], v[122:125]
	v_mfma_f32_16x16x32_bf16 v[106:109], v[138:141], v[194:197], v[106:109]
	v_mfma_f32_16x16x32_bf16 v[110:113], v[130:133], v[194:197], v[110:113]
	v_mfma_f32_16x16x32_bf16 v[94:97], v[130:133], v[202:205], v[94:97]
	v_mfma_f32_16x16x32_bf16 v[90:93], v[138:141], v[202:205], v[90:93]
	v_mfma_f32_16x16x32_bf16 v[74:77], v[138:141], v[212:215], v[74:77]
	v_mfma_f32_16x16x32_bf16 v[78:81], v[130:133], v[212:215], v[78:81]
	v_mfma_f32_16x16x32_bf16 v[126:129], v[134:137], v[190:193], v[126:129]
	v_mfma_f32_16x16x32_bf16 v[122:125], v[142:145], v[190:193], v[122:125]
	v_mfma_f32_16x16x32_bf16 v[106:109], v[142:145], v[198:201], v[106:109]
	v_mfma_f32_16x16x32_bf16 v[110:113], v[134:137], v[198:201], v[110:113]
	v_mfma_f32_16x16x32_bf16 v[94:97], v[134:137], v[206:209], v[94:97]
	v_mfma_f32_16x16x32_bf16 v[90:93], v[142:145], v[206:209], v[90:93]
	v_mfma_f32_16x16x32_bf16 v[74:77], v[142:145], v[216:219], v[74:77]
	v_mfma_f32_16x16x32_bf16 v[78:81], v[134:137], v[216:219], v[78:81]
	v_mfma_f32_16x16x32_bf16 v[118:121], v[170:173], v[186:189], v[118:121]
	v_mfma_f32_16x16x32_bf16 v[114:117], v[178:181], v[186:189], v[114:117]
	v_mfma_f32_16x16x32_bf16 v[98:101], v[178:181], v[194:197], v[98:101]
	v_mfma_f32_16x16x32_bf16 v[102:105], v[170:173], v[194:197], v[102:105]
	v_mfma_f32_16x16x32_bf16 v[86:89], v[170:173], v[202:205], v[86:89]
	v_mfma_f32_16x16x32_bf16 v[82:85], v[178:181], v[202:205], v[82:85]
	v_mfma_f32_16x16x32_bf16 v[66:69], v[178:181], v[212:215], v[66:69]
	v_mfma_f32_16x16x32_bf16 v[70:73], v[170:173], v[212:215], v[70:73]
	v_mfma_f32_16x16x32_bf16 v[118:121], v[174:177], v[190:193], v[118:121]
	v_mfma_f32_16x16x32_bf16 v[114:117], v[182:185], v[190:193], v[114:117]
	v_mfma_f32_16x16x32_bf16 v[98:101], v[182:185], v[198:201], v[98:101]
	v_mfma_f32_16x16x32_bf16 v[102:105], v[174:177], v[198:201], v[102:105]
	v_mfma_f32_16x16x32_bf16 v[86:89], v[174:177], v[206:209], v[86:89]
	v_mfma_f32_16x16x32_bf16 v[82:85], v[182:185], v[206:209], v[82:85]
	v_mfma_f32_16x16x32_bf16 v[66:69], v[182:185], v[216:219], v[66:69]
	v_mfma_f32_16x16x32_bf16 v[70:73], v[174:177], v[216:219], v[70:73]
	s_barrier
	s_add_i32 s60, s65, s41
	v_lshl_add_u64 v[220:221], s[36:37], 0, v[150:151]
	s_mov_b32 m0, s60
	ds_read_b128 v[186:189], v168 offset:16384
	ds_read_b128 v[190:193], v168 offset:17408
	ds_read_b128 v[194:197], v168 offset:18432
	ds_read_b128 v[198:201], v168 offset:19456
	ds_read_b128 v[202:205], v168 offset:20480
	ds_read_b128 v[206:209], v168 offset:21504
	ds_read_b128 v[212:215], v168 offset:22528
	ds_read_b128 v[216:219], v168 offset:23552
	global_load_lds_dwordx4 v[220:221], off
	s_add_i32 m0, s60, 0x2000
	s_add_u32 s60, s36, 0x40000
	v_lshl_add_u64 v[222:223], s[36:37], 0, v[146:147]
	s_addc_u32 s61, s37, 0
	s_add_i32 s76, s66, s41
	global_load_lds_dwordx4 v[222:223], off
	v_lshl_add_u64 v[224:225], s[60:61], 0, v[150:151]
	s_mov_b32 m0, s76
	v_lshl_add_u64 v[226:227], s[38:39], 0, v[148:149]
	global_load_lds_dwordx4 v[224:225], off
	v_lshl_add_u64 v[224:225], s[60:61], 0, v[146:147]
	s_add_i32 m0, s76, 0x2000
	s_nop 0
	global_load_lds_dwordx4 v[224:225], off
	v_lshl_add_u64 v[224:225], s[38:39], 0, v[152:153]
	s_mov_b32 m0, s29
	s_nop 0
	global_load_lds_dwordx4 v[224:225], off
	s_mov_b32 m0, s45
	s_nop 0
	global_load_lds_dwordx4 v[226:227], off
	s_waitcnt vmcnt(8)
	s_waitcnt lgkmcnt(0)
	s_barrier
	s_waitcnt lgkmcnt(0)
	v_mfma_f32_16x16x32_bf16 v[62:65], v[130:133], v[186:189], v[62:65]
	v_mfma_f32_16x16x32_bf16 v[58:61], v[138:141], v[186:189], v[58:61]
	v_mfma_f32_16x16x32_bf16 v[42:45], v[138:141], v[194:197], v[42:45]
	v_mfma_f32_16x16x32_bf16 v[46:49], v[130:133], v[194:197], v[46:49]
	v_mfma_f32_16x16x32_bf16 v[30:33], v[130:133], v[202:205], v[30:33]
	v_mfma_f32_16x16x32_bf16 v[26:29], v[138:141], v[202:205], v[26:29]
	v_mfma_f32_16x16x32_bf16 v[10:13], v[138:141], v[212:215], v[10:13]
	v_mfma_f32_16x16x32_bf16 v[14:17], v[130:133], v[212:215], v[14:17]
	v_mfma_f32_16x16x32_bf16 v[62:65], v[134:137], v[190:193], v[62:65]
	v_mfma_f32_16x16x32_bf16 v[58:61], v[142:145], v[190:193], v[58:61]
	v_mfma_f32_16x16x32_bf16 v[42:45], v[142:145], v[198:201], v[42:45]
	v_mfma_f32_16x16x32_bf16 v[46:49], v[134:137], v[198:201], v[46:49]
	v_mfma_f32_16x16x32_bf16 v[30:33], v[134:137], v[206:209], v[30:33]
	v_mfma_f32_16x16x32_bf16 v[26:29], v[142:145], v[206:209], v[26:29]
	v_mfma_f32_16x16x32_bf16 v[10:13], v[142:145], v[216:219], v[10:13]
	v_mfma_f32_16x16x32_bf16 v[14:17], v[134:137], v[216:219], v[14:17]
	v_mfma_f32_16x16x32_bf16 v[54:57], v[170:173], v[186:189], v[54:57]
	v_mfma_f32_16x16x32_bf16 v[50:53], v[178:181], v[186:189], v[50:53]
	v_mfma_f32_16x16x32_bf16 v[34:37], v[178:181], v[194:197], v[34:37]
	v_mfma_f32_16x16x32_bf16 v[38:41], v[170:173], v[194:197], v[38:41]
	v_mfma_f32_16x16x32_bf16 v[22:25], v[170:173], v[202:205], v[22:25]
	v_mfma_f32_16x16x32_bf16 v[18:21], v[178:181], v[202:205], v[18:21]
	v_mfma_f32_16x16x32_bf16 v[2:5], v[178:181], v[212:215], v[2:5]
	v_mfma_f32_16x16x32_bf16 v[6:9], v[170:173], v[212:215], v[6:9]
	v_mfma_f32_16x16x32_bf16 v[54:57], v[174:177], v[190:193], v[54:57]
	v_mfma_f32_16x16x32_bf16 v[50:53], v[182:185], v[190:193], v[50:53]
	v_mfma_f32_16x16x32_bf16 v[34:37], v[182:185], v[198:201], v[34:37]
	v_mfma_f32_16x16x32_bf16 v[38:41], v[174:177], v[198:201], v[38:41]
	v_mfma_f32_16x16x32_bf16 v[22:25], v[174:177], v[206:209], v[22:25]
	v_mfma_f32_16x16x32_bf16 v[18:21], v[182:185], v[206:209], v[18:21]
	v_mfma_f32_16x16x32_bf16 v[2:5], v[182:185], v[216:219], v[2:5]
	v_mfma_f32_16x16x32_bf16 v[6:9], v[174:177], v[216:219], v[6:9]
	s_barrier
	s_add_i32 s60, 0, 0x18000
	s_add_i32 s61, 0, 0x1c000
	v_add_u32_e32 v142, s60, v164
	v_add_u32_e32 v169, s61, v164
	ds_read_b128 v[130:133], v142
	ds_read_b128 v[134:137], v142 offset:1024
	ds_read_b128 v[138:141], v142 offset:2048
	ds_read_b128 v[142:145], v142 offset:3072
	ds_read_b128 v[170:173], v169
	ds_read_b128 v[174:177], v169 offset:1024
	ds_read_b128 v[178:181], v169 offset:2048
	ds_read_b128 v[182:185], v169 offset:3072
	s_add_u32 s38, s38, 0x40000
	s_addc_u32 s39, s39, 0
	s_mov_b32 m0, s46
	v_lshl_add_u64 v[228:229], s[38:39], 0, v[152:153]
	ds_read_b128 v[186:189], v168 offset:32768
	ds_read_b128 v[190:193], v168 offset:33792
	ds_read_b128 v[194:197], v168 offset:34816
	ds_read_b128 v[198:201], v168 offset:35840
	ds_read_b128 v[202:205], v168 offset:36864
	ds_read_b128 v[206:209], v168 offset:37888
	ds_read_b128 v[212:215], v168 offset:38912
	ds_read_b128 v[216:219], v168 offset:39936
	global_load_lds_dwordx4 v[228:229], off
	v_lshl_add_u64 v[228:229], s[38:39], 0, v[148:149]
	s_mov_b32 m0, s47
	s_nop 0
	global_load_lds_dwordx4 v[228:229], off
	s_waitcnt vmcnt(8)
	s_waitcnt lgkmcnt(0)
	s_barrier
	s_waitcnt lgkmcnt(0)
	v_mfma_f32_16x16x32_bf16 v[126:129], v[130:133], v[186:189], v[126:129]
	v_mfma_f32_16x16x32_bf16 v[122:125], v[138:141], v[186:189], v[122:125]
	v_mfma_f32_16x16x32_bf16 v[106:109], v[138:141], v[194:197], v[106:109]
	v_mfma_f32_16x16x32_bf16 v[110:113], v[130:133], v[194:197], v[110:113]
	v_mfma_f32_16x16x32_bf16 v[94:97], v[130:133], v[202:205], v[94:97]
	v_mfma_f32_16x16x32_bf16 v[90:93], v[138:141], v[202:205], v[90:93]
	v_mfma_f32_16x16x32_bf16 v[74:77], v[138:141], v[212:215], v[74:77]
	v_mfma_f32_16x16x32_bf16 v[78:81], v[130:133], v[212:215], v[78:81]
	v_mfma_f32_16x16x32_bf16 v[126:129], v[134:137], v[190:193], v[126:129]
	v_mfma_f32_16x16x32_bf16 v[122:125], v[142:145], v[190:193], v[122:125]
	v_mfma_f32_16x16x32_bf16 v[106:109], v[142:145], v[198:201], v[106:109]
	v_mfma_f32_16x16x32_bf16 v[110:113], v[134:137], v[198:201], v[110:113]
	v_mfma_f32_16x16x32_bf16 v[94:97], v[134:137], v[206:209], v[94:97]
	v_mfma_f32_16x16x32_bf16 v[90:93], v[142:145], v[206:209], v[90:93]
	v_mfma_f32_16x16x32_bf16 v[74:77], v[142:145], v[216:219], v[74:77]
	v_mfma_f32_16x16x32_bf16 v[78:81], v[134:137], v[216:219], v[78:81]
	v_mfma_f32_16x16x32_bf16 v[118:121], v[170:173], v[186:189], v[118:121]
	v_mfma_f32_16x16x32_bf16 v[114:117], v[178:181], v[186:189], v[114:117]
	v_mfma_f32_16x16x32_bf16 v[98:101], v[178:181], v[194:197], v[98:101]
	v_mfma_f32_16x16x32_bf16 v[102:105], v[170:173], v[194:197], v[102:105]
	v_mfma_f32_16x16x32_bf16 v[86:89], v[170:173], v[202:205], v[86:89]
	v_mfma_f32_16x16x32_bf16 v[82:85], v[178:181], v[202:205], v[82:85]
	v_mfma_f32_16x16x32_bf16 v[66:69], v[178:181], v[212:215], v[66:69]
	v_mfma_f32_16x16x32_bf16 v[70:73], v[170:173], v[212:215], v[70:73]
	v_mfma_f32_16x16x32_bf16 v[118:121], v[174:177], v[190:193], v[118:121]
	v_mfma_f32_16x16x32_bf16 v[114:117], v[182:185], v[190:193], v[114:117]
	v_mfma_f32_16x16x32_bf16 v[98:101], v[182:185], v[198:201], v[98:101]
	v_mfma_f32_16x16x32_bf16 v[102:105], v[174:177], v[198:201], v[102:105]
	v_mfma_f32_16x16x32_bf16 v[86:89], v[174:177], v[206:209], v[86:89]
	v_mfma_f32_16x16x32_bf16 v[82:85], v[182:185], v[206:209], v[82:85]
	v_mfma_f32_16x16x32_bf16 v[66:69], v[182:185], v[216:219], v[66:69]
	v_mfma_f32_16x16x32_bf16 v[70:73], v[174:177], v[216:219], v[70:73]
	s_barrier
	s_add_i32 s38, s60, s41
	v_lshl_add_u64 v[220:221], v[220:221], 0, s[10:11]
	s_mov_b32 m0, s38
	ds_read_b128 v[186:189], v168 offset:49152
	ds_read_b128 v[190:193], v168 offset:50176
	ds_read_b128 v[194:197], v168 offset:51200
	ds_read_b128 v[198:201], v168 offset:52224
	ds_read_b128 v[202:205], v168 offset:53248
	ds_read_b128 v[206:209], v168 offset:54272
	ds_read_b128 v[212:215], v168 offset:55296
	ds_read_b128 v[216:219], v168 offset:56320
	global_load_lds_dwordx4 v[220:221], off
	s_add_i32 m0, s38, 0x2000
	s_add_u32 s36, s36, 0x40080
	v_lshl_add_u64 v[220:221], v[222:223], 0, s[10:11]
	s_addc_u32 s37, s37, 0
	s_add_i32 s38, s61, s41
	global_load_lds_dwordx4 v[220:221], off
	v_lshl_add_u64 v[220:221], s[36:37], 0, v[150:151]
	s_mov_b32 m0, s38
	s_nop 0
	global_load_lds_dwordx4 v[220:221], off
	v_lshl_add_u64 v[220:221], s[36:37], 0, v[146:147]
	s_add_i32 m0, s38, 0x2000
	s_nop 0
	global_load_lds_dwordx4 v[220:221], off
	v_lshl_add_u64 v[220:221], v[224:225], 0, s[10:11]
	s_mov_b32 m0, s63
	s_nop 0
	global_load_lds_dwordx4 v[220:221], off
	v_lshl_add_u64 v[220:221], v[226:227], 0, s[10:11]
	s_mov_b32 m0, s64
	s_nop 0
	global_load_lds_dwordx4 v[220:221], off
	s_waitcnt vmcnt(8)
	s_waitcnt lgkmcnt(0)
	s_barrier
	s_waitcnt lgkmcnt(0)
	v_mfma_f32_16x16x32_bf16 v[62:65], v[130:133], v[186:189], v[62:65]
	v_mfma_f32_16x16x32_bf16 v[58:61], v[138:141], v[186:189], v[58:61]
	v_mfma_f32_16x16x32_bf16 v[42:45], v[138:141], v[194:197], v[42:45]
	v_mfma_f32_16x16x32_bf16 v[46:49], v[130:133], v[194:197], v[46:49]
	v_mfma_f32_16x16x32_bf16 v[30:33], v[130:133], v[202:205], v[30:33]
	v_mfma_f32_16x16x32_bf16 v[26:29], v[138:141], v[202:205], v[26:29]
	v_mfma_f32_16x16x32_bf16 v[10:13], v[138:141], v[212:215], v[10:13]
	v_mfma_f32_16x16x32_bf16 v[14:17], v[130:133], v[212:215], v[14:17]
	v_mfma_f32_16x16x32_bf16 v[62:65], v[134:137], v[190:193], v[62:65]
	v_mfma_f32_16x16x32_bf16 v[58:61], v[142:145], v[190:193], v[58:61]
	v_mfma_f32_16x16x32_bf16 v[42:45], v[142:145], v[198:201], v[42:45]
	v_mfma_f32_16x16x32_bf16 v[46:49], v[134:137], v[198:201], v[46:49]
	v_mfma_f32_16x16x32_bf16 v[30:33], v[134:137], v[206:209], v[30:33]
	v_mfma_f32_16x16x32_bf16 v[26:29], v[142:145], v[206:209], v[26:29]
	v_mfma_f32_16x16x32_bf16 v[10:13], v[142:145], v[216:219], v[10:13]
	v_mfma_f32_16x16x32_bf16 v[14:17], v[134:137], v[216:219], v[14:17]
	v_mfma_f32_16x16x32_bf16 v[54:57], v[170:173], v[186:189], v[54:57]
	v_mfma_f32_16x16x32_bf16 v[50:53], v[178:181], v[186:189], v[50:53]
	v_mfma_f32_16x16x32_bf16 v[34:37], v[178:181], v[194:197], v[34:37]
	v_mfma_f32_16x16x32_bf16 v[38:41], v[170:173], v[194:197], v[38:41]
	v_mfma_f32_16x16x32_bf16 v[22:25], v[170:173], v[202:205], v[22:25]
	v_mfma_f32_16x16x32_bf16 v[18:21], v[178:181], v[202:205], v[18:21]
	v_mfma_f32_16x16x32_bf16 v[2:5], v[178:181], v[212:215], v[2:5]
	v_mfma_f32_16x16x32_bf16 v[6:9], v[170:173], v[212:215], v[6:9]
	v_mfma_f32_16x16x32_bf16 v[54:57], v[174:177], v[190:193], v[54:57]
	v_mfma_f32_16x16x32_bf16 v[50:53], v[182:185], v[190:193], v[50:53]
	v_mfma_f32_16x16x32_bf16 v[34:37], v[182:185], v[198:201], v[34:37]
	v_mfma_f32_16x16x32_bf16 v[38:41], v[174:177], v[198:201], v[38:41]
	v_mfma_f32_16x16x32_bf16 v[22:25], v[174:177], v[206:209], v[22:25]
	v_mfma_f32_16x16x32_bf16 v[18:21], v[182:185], v[206:209], v[18:21]
	v_mfma_f32_16x16x32_bf16 v[2:5], v[182:185], v[216:219], v[2:5]
	v_mfma_f32_16x16x32_bf16 v[6:9], v[174:177], v[216:219], v[6:9]
	s_barrier
	s_add_i32 s75, s75, 2
	s_add_u32 s30, s30, 0x100
	s_addc_u32 s31, s31, 0
	s_add_u32 s73, s73, 0x100
	s_addc_u32 s74, s74, 0
	s_cmp_gt_u32 s75, 13
	s_cbranch_scc0 .LBB0_584
	s_and_b64 vcc, exec, s[12:13]
	s_cbranch_vccz .LBB0_587
	s_barrier

.LBB0_665:
	ds_read_b128 v[82:85], v169
	ds_read_b128 v[86:89], v169 offset:1024
	ds_read_b128 v[90:93], v169 offset:2048
	ds_read_b128 v[94:97], v169 offset:3072
	ds_read_b128 v[162:165], v170
	ds_read_b128 v[174:177], v170 offset:1024
	ds_read_b128 v[178:181], v170 offset:2048
	ds_read_b128 v[182:185], v170 offset:3072
	s_add_u32 s30, s28, 0xfff50080
	s_addc_u32 s31, s29, -1
	s_cmp_eq_u32 s75, 40
	s_cselect_b32 s37, s7, s31
	s_cselect_b32 s36, s6, s30
	s_cselect_b32 s31, s25, s74
	s_cselect_b32 s30, s24, s73
	v_lshl_add_u64 v[220:221], s[28:29], 0, v[154:155]
	s_add_i32 m0, s42, 0xc000
	ds_read_b128 v[186:189], v171
	ds_read_b128 v[190:193], v171 offset:1024
	ds_read_b128 v[194:197], v171 offset:2048
	ds_read_b128 v[198:201], v171 offset:3072
	ds_read_b128 v[202:205], v171 offset:4096
	ds_read_b128 v[206:209], v171 offset:5120
	ds_read_b128 v[212:215], v171 offset:6144
	ds_read_b128 v[216:219], v171 offset:7168
	global_load_lds_dwordx4 v[220:221], off
	v_lshl_add_u64 v[220:221], s[28:29], 0, v[156:157]
	s_add_i32 m0, s42, 0xe000
	s_nop 0
	global_load_lds_dwordx4 v[220:221], off
	s_waitcnt vmcnt(8)
	s_waitcnt lgkmcnt(0)
	s_barrier
	s_waitcnt lgkmcnt(0)
	v_mfma_f32_16x16x32_bf16 v[142:145], v[82:85], v[186:189], v[142:145]
	v_mfma_f32_16x16x32_bf16 v[138:141], v[90:93], v[186:189], v[138:141]
	v_mfma_f32_16x16x32_bf16 v[122:125], v[90:93], v[194:197], v[122:125]
	v_mfma_f32_16x16x32_bf16 v[126:129], v[82:85], v[194:197], v[126:129]
	v_mfma_f32_16x16x32_bf16 v[110:113], v[82:85], v[202:205], v[110:113]
	v_mfma_f32_16x16x32_bf16 v[106:109], v[90:93], v[202:205], v[106:109]
	v_mfma_f32_16x16x32_bf16 v[74:77], v[90:93], v[212:215], v[74:77]
	v_mfma_f32_16x16x32_bf16 v[78:81], v[82:85], v[212:215], v[78:81]
	v_mfma_f32_16x16x32_bf16 v[142:145], v[86:89], v[190:193], v[142:145]
	v_mfma_f32_16x16x32_bf16 v[138:141], v[94:97], v[190:193], v[138:141]
	v_mfma_f32_16x16x32_bf16 v[122:125], v[94:97], v[198:201], v[122:125]
	v_mfma_f32_16x16x32_bf16 v[126:129], v[86:89], v[198:201], v[126:129]
	v_mfma_f32_16x16x32_bf16 v[110:113], v[86:89], v[206:209], v[110:113]
	v_mfma_f32_16x16x32_bf16 v[106:109], v[94:97], v[206:209], v[106:109]
	v_mfma_f32_16x16x32_bf16 v[74:77], v[94:97], v[216:219], v[74:77]
	v_mfma_f32_16x16x32_bf16 v[78:81], v[86:89], v[216:219], v[78:81]
	v_mfma_f32_16x16x32_bf16 v[134:137], v[162:165], v[186:189], v[134:137]
	v_mfma_f32_16x16x32_bf16 v[130:133], v[178:181], v[186:189], v[130:133]
	v_mfma_f32_16x16x32_bf16 v[114:117], v[178:181], v[194:197], v[114:117]
	v_mfma_f32_16x16x32_bf16 v[118:121], v[162:165], v[194:197], v[118:121]
	v_mfma_f32_16x16x32_bf16 v[102:105], v[162:165], v[202:205], v[102:105]
	v_mfma_f32_16x16x32_bf16 v[98:101], v[178:181], v[202:205], v[98:101]
	v_mfma_f32_16x16x32_bf16 v[66:69], v[178:181], v[212:215], v[66:69]
	v_mfma_f32_16x16x32_bf16 v[70:73], v[162:165], v[212:215], v[70:73]
	v_mfma_f32_16x16x32_bf16 v[134:137], v[174:177], v[190:193], v[134:137]
	v_mfma_f32_16x16x32_bf16 v[130:133], v[182:185], v[190:193], v[130:133]
	v_mfma_f32_16x16x32_bf16 v[114:117], v[182:185], v[198:201], v[114:117]
	v_mfma_f32_16x16x32_bf16 v[118:121], v[174:177], v[198:201], v[118:121]
	v_mfma_f32_16x16x32_bf16 v[102:105], v[174:177], v[206:209], v[102:105]
	v_mfma_f32_16x16x32_bf16 v[98:101], v[182:185], v[206:209], v[98:101]
	v_mfma_f32_16x16x32_bf16 v[66:69], v[182:185], v[216:219], v[66:69]
	v_mfma_f32_16x16x32_bf16 v[70:73], v[174:177], v[216:219], v[70:73]
	s_barrier
	s_add_i32 s60, s67, s41
	v_lshl_add_u64 v[220:221], s[30:31], 0, v[148:149]
	s_mov_b32 m0, s60
	ds_read_b128 v[186:189], v171 offset:16384
	ds_read_b128 v[190:193], v171 offset:17408
	ds_read_b128 v[194:197], v171 offset:18432
	ds_read_b128 v[198:201], v171 offset:19456
	ds_read_b128 v[202:205], v171 offset:20480
	ds_read_b128 v[206:209], v171 offset:21504
	ds_read_b128 v[212:215], v171 offset:22528
	ds_read_b128 v[216:219], v171 offset:23552
	global_load_lds_dwordx4 v[220:221], off
	s_add_i32 m0, s60, 0x2000
	s_add_u32 s60, s30, 0xb0000
	v_lshl_add_u64 v[222:223], s[30:31], 0, v[152:153]
	s_addc_u32 s61, s31, 0
	s_add_i32 s76, s68, s41
	global_load_lds_dwordx4 v[222:223], off
	v_lshl_add_u64 v[224:225], s[60:61], 0, v[148:149]
	s_mov_b32 m0, s76
	v_lshl_add_u64 v[226:227], s[36:37], 0, v[150:151]
	global_load_lds_dwordx4 v[224:225], off
	v_lshl_add_u64 v[224:225], s[60:61], 0, v[152:153]
	s_add_i32 m0, s76, 0x2000
	s_nop 0
	global_load_lds_dwordx4 v[224:225], off
	v_lshl_add_u64 v[224:225], s[36:37], 0, v[146:147]
	s_mov_b32 m0, s42
	s_nop 0
	global_load_lds_dwordx4 v[224:225], off
	s_mov_b32 m0, s43
	s_nop 0
	global_load_lds_dwordx4 v[226:227], off
	s_waitcnt vmcnt(8)
	s_waitcnt lgkmcnt(0)
	s_barrier
	s_waitcnt lgkmcnt(0)
	v_mfma_f32_16x16x32_bf16 v[62:65], v[82:85], v[186:189], v[62:65]
	v_mfma_f32_16x16x32_bf16 v[58:61], v[90:93], v[186:189], v[58:61]
	v_mfma_f32_16x16x32_bf16 v[42:45], v[90:93], v[194:197], v[42:45]
	v_mfma_f32_16x16x32_bf16 v[46:49], v[82:85], v[194:197], v[46:49]
	v_mfma_f32_16x16x32_bf16 v[30:33], v[82:85], v[202:205], v[30:33]
	v_mfma_f32_16x16x32_bf16 v[26:29], v[90:93], v[202:205], v[26:29]
	v_mfma_f32_16x16x32_bf16 v[10:13], v[90:93], v[212:215], v[10:13]
	v_mfma_f32_16x16x32_bf16 v[14:17], v[82:85], v[212:215], v[14:17]
	v_mfma_f32_16x16x32_bf16 v[62:65], v[86:89], v[190:193], v[62:65]
	v_mfma_f32_16x16x32_bf16 v[58:61], v[94:97], v[190:193], v[58:61]
	v_mfma_f32_16x16x32_bf16 v[42:45], v[94:97], v[198:201], v[42:45]
	v_mfma_f32_16x16x32_bf16 v[46:49], v[86:89], v[198:201], v[46:49]
	v_mfma_f32_16x16x32_bf16 v[30:33], v[86:89], v[206:209], v[30:33]
	v_mfma_f32_16x16x32_bf16 v[26:29], v[94:97], v[206:209], v[26:29]
	v_mfma_f32_16x16x32_bf16 v[10:13], v[94:97], v[216:219], v[10:13]
	v_mfma_f32_16x16x32_bf16 v[14:17], v[86:89], v[216:219], v[14:17]
	v_mfma_f32_16x16x32_bf16 v[54:57], v[162:165], v[186:189], v[54:57]
	v_mfma_f32_16x16x32_bf16 v[50:53], v[178:181], v[186:189], v[50:53]
	v_mfma_f32_16x16x32_bf16 v[34:37], v[178:181], v[194:197], v[34:37]
	v_mfma_f32_16x16x32_bf16 v[38:41], v[162:165], v[194:197], v[38:41]
	v_mfma_f32_16x16x32_bf16 v[22:25], v[162:165], v[202:205], v[22:25]
	v_mfma_f32_16x16x32_bf16 v[18:21], v[178:181], v[202:205], v[18:21]
	v_mfma_f32_16x16x32_bf16 v[2:5], v[178:181], v[212:215], v[2:5]
	v_mfma_f32_16x16x32_bf16 v[6:9], v[162:165], v[212:215], v[6:9]
	v_mfma_f32_16x16x32_bf16 v[54:57], v[174:177], v[190:193], v[54:57]
	v_mfma_f32_16x16x32_bf16 v[50:53], v[182:185], v[190:193], v[50:53]
	v_mfma_f32_16x16x32_bf16 v[34:37], v[182:185], v[198:201], v[34:37]
	v_mfma_f32_16x16x32_bf16 v[38:41], v[174:177], v[198:201], v[38:41]
	v_mfma_f32_16x16x32_bf16 v[22:25], v[174:177], v[206:209], v[22:25]
	v_mfma_f32_16x16x32_bf16 v[18:21], v[182:185], v[206:209], v[18:21]
	v_mfma_f32_16x16x32_bf16 v[2:5], v[182:185], v[216:219], v[2:5]
	v_mfma_f32_16x16x32_bf16 v[6:9], v[174:177], v[216:219], v[6:9]
	s_barrier
	s_add_i32 s60, 0, 0x18000
	s_add_i32 s61, 0, 0x1c000
	v_add_u32_e32 v94, s60, v167
	v_add_u32_e32 v173, s61, v167
	ds_read_b128 v[82:85], v94
	ds_read_b128 v[86:89], v94 offset:1024
	ds_read_b128 v[90:93], v94 offset:2048
	ds_read_b128 v[94:97], v94 offset:3072
	ds_read_b128 v[162:165], v173
	ds_read_b128 v[174:177], v173 offset:1024
	ds_read_b128 v[178:181], v173 offset:2048
	ds_read_b128 v[182:185], v173 offset:3072
	s_add_u32 s36, s36, 0xb0000
	s_addc_u32 s37, s37, 0
	s_mov_b32 m0, s44
	v_lshl_add_u64 v[228:229], s[36:37], 0, v[146:147]
	ds_read_b128 v[186:189], v171 offset:32768
	ds_read_b128 v[190:193], v171 offset:33792
	ds_read_b128 v[194:197], v171 offset:34816
	ds_read_b128 v[198:201], v171 offset:35840
	ds_read_b128 v[202:205], v171 offset:36864
	ds_read_b128 v[206:209], v171 offset:37888
	ds_read_b128 v[212:215], v171 offset:38912
	ds_read_b128 v[216:219], v171 offset:39936
	global_load_lds_dwordx4 v[228:229], off
	v_lshl_add_u64 v[228:229], s[36:37], 0, v[150:151]
	s_mov_b32 m0, s45
	s_nop 0
	global_load_lds_dwordx4 v[228:229], off
	s_waitcnt vmcnt(8)
	s_waitcnt lgkmcnt(0)
	s_barrier
	s_waitcnt lgkmcnt(0)
	v_mfma_f32_16x16x32_bf16 v[142:145], v[82:85], v[186:189], v[142:145]
	v_mfma_f32_16x16x32_bf16 v[138:141], v[90:93], v[186:189], v[138:141]
	v_mfma_f32_16x16x32_bf16 v[122:125], v[90:93], v[194:197], v[122:125]
	v_mfma_f32_16x16x32_bf16 v[126:129], v[82:85], v[194:197], v[126:129]
	v_mfma_f32_16x16x32_bf16 v[110:113], v[82:85], v[202:205], v[110:113]
	v_mfma_f32_16x16x32_bf16 v[106:109], v[90:93], v[202:205], v[106:109]
	v_mfma_f32_16x16x32_bf16 v[74:77], v[90:93], v[212:215], v[74:77]
	v_mfma_f32_16x16x32_bf16 v[78:81], v[82:85], v[212:215], v[78:81]
	v_mfma_f32_16x16x32_bf16 v[142:145], v[86:89], v[190:193], v[142:145]
	v_mfma_f32_16x16x32_bf16 v[138:141], v[94:97], v[190:193], v[138:141]
	v_mfma_f32_16x16x32_bf16 v[122:125], v[94:97], v[198:201], v[122:125]
	v_mfma_f32_16x16x32_bf16 v[126:129], v[86:89], v[198:201], v[126:129]
	v_mfma_f32_16x16x32_bf16 v[110:113], v[86:89], v[206:209], v[110:113]
	v_mfma_f32_16x16x32_bf16 v[106:109], v[94:97], v[206:209], v[106:109]
	v_mfma_f32_16x16x32_bf16 v[74:77], v[94:97], v[216:219], v[74:77]
	v_mfma_f32_16x16x32_bf16 v[78:81], v[86:89], v[216:219], v[78:81]
	v_mfma_f32_16x16x32_bf16 v[134:137], v[162:165], v[186:189], v[134:137]
	v_mfma_f32_16x16x32_bf16 v[130:133], v[178:181], v[186:189], v[130:133]
	v_mfma_f32_16x16x32_bf16 v[114:117], v[178:181], v[194:197], v[114:117]
	v_mfma_f32_16x16x32_bf16 v[118:121], v[162:165], v[194:197], v[118:121]
	v_mfma_f32_16x16x32_bf16 v[102:105], v[162:165], v[202:205], v[102:105]
	v_mfma_f32_16x16x32_bf16 v[98:101], v[178:181], v[202:205], v[98:101]
	v_mfma_f32_16x16x32_bf16 v[66:69], v[178:181], v[212:215], v[66:69]
	v_mfma_f32_16x16x32_bf16 v[70:73], v[162:165], v[212:215], v[70:73]
	v_mfma_f32_16x16x32_bf16 v[134:137], v[174:177], v[190:193], v[134:137]
	v_mfma_f32_16x16x32_bf16 v[130:133], v[182:185], v[190:193], v[130:133]
	v_mfma_f32_16x16x32_bf16 v[114:117], v[182:185], v[198:201], v[114:117]
	v_mfma_f32_16x16x32_bf16 v[118:121], v[174:177], v[198:201], v[118:121]
	v_mfma_f32_16x16x32_bf16 v[102:105], v[174:177], v[206:209], v[102:105]
	v_mfma_f32_16x16x32_bf16 v[98:101], v[182:185], v[206:209], v[98:101]
	v_mfma_f32_16x16x32_bf16 v[66:69], v[182:185], v[216:219], v[66:69]
	v_mfma_f32_16x16x32_bf16 v[70:73], v[174:177], v[216:219], v[70:73]
	s_barrier
	s_add_i32 s36, s60, s41
	v_lshl_add_u64 v[220:221], v[220:221], 0, s[16:17]
	s_mov_b32 m0, s36
	ds_read_b128 v[186:189], v171 offset:49152
	ds_read_b128 v[190:193], v171 offset:50176
	ds_read_b128 v[194:197], v171 offset:51200
	ds_read_b128 v[198:201], v171 offset:52224
	ds_read_b128 v[202:205], v171 offset:53248
	ds_read_b128 v[206:209], v171 offset:54272
	ds_read_b128 v[212:215], v171 offset:55296
	ds_read_b128 v[216:219], v171 offset:56320
	global_load_lds_dwordx4 v[220:221], off
	s_add_i32 m0, s36, 0x2000
	s_add_u32 s30, s30, 0xb0080
	v_lshl_add_u64 v[220:221], v[222:223], 0, s[16:17]
	s_addc_u32 s31, s31, 0
	s_add_i32 s36, s61, s41
	global_load_lds_dwordx4 v[220:221], off
	v_lshl_add_u64 v[220:221], s[30:31], 0, v[148:149]
	s_mov_b32 m0, s36
	s_nop 0
	global_load_lds_dwordx4 v[220:221], off
	v_lshl_add_u64 v[220:221], s[30:31], 0, v[152:153]
	s_add_i32 m0, s36, 0x2000
	s_nop 0
	global_load_lds_dwordx4 v[220:221], off
	v_lshl_add_u64 v[220:221], v[224:225], 0, s[16:17]
	s_mov_b32 m0, s64
	s_nop 0
	global_load_lds_dwordx4 v[220:221], off
	v_lshl_add_u64 v[220:221], v[226:227], 0, s[16:17]
	s_mov_b32 m0, s65
	s_nop 0
	global_load_lds_dwordx4 v[220:221], off
	s_waitcnt vmcnt(8)
	s_waitcnt lgkmcnt(0)
	s_barrier
	s_waitcnt lgkmcnt(0)
	v_mfma_f32_16x16x32_bf16 v[62:65], v[82:85], v[186:189], v[62:65]
	v_mfma_f32_16x16x32_bf16 v[58:61], v[90:93], v[186:189], v[58:61]
	v_mfma_f32_16x16x32_bf16 v[42:45], v[90:93], v[194:197], v[42:45]
	v_mfma_f32_16x16x32_bf16 v[46:49], v[82:85], v[194:197], v[46:49]
	v_mfma_f32_16x16x32_bf16 v[30:33], v[82:85], v[202:205], v[30:33]
	v_mfma_f32_16x16x32_bf16 v[26:29], v[90:93], v[202:205], v[26:29]
	v_mfma_f32_16x16x32_bf16 v[10:13], v[90:93], v[212:215], v[10:13]
	v_mfma_f32_16x16x32_bf16 v[14:17], v[82:85], v[212:215], v[14:17]
	v_mfma_f32_16x16x32_bf16 v[62:65], v[86:89], v[190:193], v[62:65]
	v_mfma_f32_16x16x32_bf16 v[58:61], v[94:97], v[190:193], v[58:61]
	v_mfma_f32_16x16x32_bf16 v[42:45], v[94:97], v[198:201], v[42:45]
	v_mfma_f32_16x16x32_bf16 v[46:49], v[86:89], v[198:201], v[46:49]
	v_mfma_f32_16x16x32_bf16 v[30:33], v[86:89], v[206:209], v[30:33]
	v_mfma_f32_16x16x32_bf16 v[26:29], v[94:97], v[206:209], v[26:29]
	v_mfma_f32_16x16x32_bf16 v[10:13], v[94:97], v[216:219], v[10:13]
	v_mfma_f32_16x16x32_bf16 v[14:17], v[86:89], v[216:219], v[14:17]
	v_mfma_f32_16x16x32_bf16 v[54:57], v[162:165], v[186:189], v[54:57]
	v_mfma_f32_16x16x32_bf16 v[50:53], v[178:181], v[186:189], v[50:53]
	v_mfma_f32_16x16x32_bf16 v[34:37], v[178:181], v[194:197], v[34:37]
	v_mfma_f32_16x16x32_bf16 v[38:41], v[162:165], v[194:197], v[38:41]
	v_mfma_f32_16x16x32_bf16 v[22:25], v[162:165], v[202:205], v[22:25]
	v_mfma_f32_16x16x32_bf16 v[18:21], v[178:181], v[202:205], v[18:21]
	v_mfma_f32_16x16x32_bf16 v[2:5], v[178:181], v[212:215], v[2:5]
	v_mfma_f32_16x16x32_bf16 v[6:9], v[162:165], v[212:215], v[6:9]
	v_mfma_f32_16x16x32_bf16 v[54:57], v[174:177], v[190:193], v[54:57]
	v_mfma_f32_16x16x32_bf16 v[50:53], v[182:185], v[190:193], v[50:53]
	v_mfma_f32_16x16x32_bf16 v[34:37], v[182:185], v[198:201], v[34:37]
	v_mfma_f32_16x16x32_bf16 v[38:41], v[174:177], v[198:201], v[38:41]
	v_mfma_f32_16x16x32_bf16 v[22:25], v[174:177], v[206:209], v[22:25]
	v_mfma_f32_16x16x32_bf16 v[18:21], v[182:185], v[206:209], v[18:21]
	v_mfma_f32_16x16x32_bf16 v[2:5], v[182:185], v[216:219], v[2:5]
	v_mfma_f32_16x16x32_bf16 v[6:9], v[174:177], v[216:219], v[6:9]
	s_barrier
	s_add_i32 s75, s75, 2
	s_add_u32 s28, s28, 0x100
	s_addc_u32 s29, s29, 0
	s_add_u32 s73, s73, 0x100
	s_addc_u32 s74, s74, 0
	s_cmp_gt_u32 s75, 41
	s_cbranch_scc0 .LBB0_665
	s_and_b64 vcc, exec, s[18:19]
	s_cbranch_vccz .LBB0_668
	s_barrier

.LBB0_911:
	ds_read_b128 v[156:159], v153
	ds_read_b128 v[160:163], v153 offset:1024
	ds_read_b128 v[164:167], v153 offset:2048
	ds_read_b128 v[168:171], v153 offset:3072
	ds_read_b128 v[172:175], v154
	ds_read_b128 v[176:179], v154 offset:1024
	ds_read_b128 v[180:183], v154 offset:2048
	ds_read_b128 v[184:187], v154 offset:3072
	s_add_u32 s42, s40, 0x100
	s_addc_u32 s43, s41, 0
	s_add_u32 s44, s77, s40
	s_addc_u32 s45, s78, s41
	s_cmp_eq_u32 s79, 4
	s_cselect_b32 s46, s37, s44
	s_cselect_b32 s44, 0, s42
	s_cselect_b32 s47, s31, s45
	s_cselect_b32 s45, 0, s43
	s_add_u32 s44, s6, s44
	s_addc_u32 s45, s7, s45
	v_lshl_add_u64 v[208:209], v[146:147], 0, s[40:41]
	s_add_i32 m0, s29, 0xc000
	ds_read_b128 v[188:191], v155
	ds_read_b128 v[192:195], v155 offset:1024
	ds_read_b128 v[196:199], v155 offset:2048
	ds_read_b128 v[200:203], v155 offset:3072
	ds_read_b128 v[204:207], v155 offset:4096
	ds_read_b128 v[212:215], v155 offset:5120
	ds_read_b128 v[216:219], v155 offset:6144
	ds_read_b128 v[220:223], v155 offset:7168
	global_load_lds_dwordx4 v[208:209], off
	v_lshl_add_u64 v[208:209], v[148:149], 0, s[40:41]
	s_add_i32 m0, s29, 0xe000
	s_nop 0
	global_load_lds_dwordx4 v[208:209], off
	s_waitcnt vmcnt(8)
	s_waitcnt lgkmcnt(0)
	s_barrier
	s_waitcnt lgkmcnt(0)
	v_mfma_f32_16x16x32_bf16 v[126:129], v[156:159], v[188:191], v[126:129]
	v_mfma_f32_16x16x32_bf16 v[122:125], v[164:167], v[188:191], v[122:125]
	v_mfma_f32_16x16x32_bf16 v[114:117], v[164:167], v[196:199], v[114:117]
	v_mfma_f32_16x16x32_bf16 v[118:121], v[156:159], v[196:199], v[118:121]
	v_mfma_f32_16x16x32_bf16 v[102:105], v[156:159], v[204:207], v[102:105]
	v_mfma_f32_16x16x32_bf16 v[98:101], v[164:167], v[204:207], v[98:101]
	v_mfma_f32_16x16x32_bf16 v[82:85], v[164:167], v[216:219], v[82:85]
	v_mfma_f32_16x16x32_bf16 v[86:89], v[156:159], v[216:219], v[86:89]
	v_mfma_f32_16x16x32_bf16 v[126:129], v[160:163], v[192:195], v[126:129]
	v_mfma_f32_16x16x32_bf16 v[122:125], v[168:171], v[192:195], v[122:125]
	v_mfma_f32_16x16x32_bf16 v[114:117], v[168:171], v[200:203], v[114:117]
	v_mfma_f32_16x16x32_bf16 v[118:121], v[160:163], v[200:203], v[118:121]
	v_mfma_f32_16x16x32_bf16 v[102:105], v[160:163], v[212:215], v[102:105]
	v_mfma_f32_16x16x32_bf16 v[98:101], v[168:171], v[212:215], v[98:101]
	v_mfma_f32_16x16x32_bf16 v[82:85], v[168:171], v[220:223], v[82:85]
	v_mfma_f32_16x16x32_bf16 v[86:89], v[160:163], v[220:223], v[86:89]
	v_mfma_f32_16x16x32_bf16 v[110:113], v[172:175], v[188:191], v[110:113]
	v_mfma_f32_16x16x32_bf16 v[106:109], v[180:183], v[188:191], v[106:109]
	v_mfma_f32_16x16x32_bf16 v[90:93], v[180:183], v[196:199], v[90:93]
	v_mfma_f32_16x16x32_bf16 v[94:97], v[172:175], v[196:199], v[94:97]
	v_mfma_f32_16x16x32_bf16 v[78:81], v[172:175], v[204:207], v[78:81]
	v_mfma_f32_16x16x32_bf16 v[74:77], v[180:183], v[204:207], v[74:77]
	v_mfma_f32_16x16x32_bf16 v[66:69], v[180:183], v[216:219], v[66:69]
	v_mfma_f32_16x16x32_bf16 v[70:73], v[172:175], v[216:219], v[70:73]
	v_mfma_f32_16x16x32_bf16 v[110:113], v[176:179], v[192:195], v[110:113]
	v_mfma_f32_16x16x32_bf16 v[106:109], v[184:187], v[192:195], v[106:109]
	v_mfma_f32_16x16x32_bf16 v[90:93], v[184:187], v[200:203], v[90:93]
	v_mfma_f32_16x16x32_bf16 v[94:97], v[176:179], v[200:203], v[94:97]
	v_mfma_f32_16x16x32_bf16 v[78:81], v[176:179], v[212:215], v[78:81]
	v_mfma_f32_16x16x32_bf16 v[74:77], v[184:187], v[212:215], v[74:77]
	v_mfma_f32_16x16x32_bf16 v[66:69], v[184:187], v[220:223], v[66:69]
	v_mfma_f32_16x16x32_bf16 v[70:73], v[176:179], v[220:223], v[70:73]
	s_barrier
	s_add_i32 s40, s70, s62
	v_lshl_add_u64 v[208:209], s[44:45], 0, v[132:133]
	s_mov_b32 m0, s40
	ds_read_b128 v[188:191], v155 offset:16384
	ds_read_b128 v[192:195], v155 offset:17408
	ds_read_b128 v[196:199], v155 offset:18432
	ds_read_b128 v[200:203], v155 offset:19456
	ds_read_b128 v[204:207], v155 offset:20480
	ds_read_b128 v[212:215], v155 offset:21504
	ds_read_b128 v[216:219], v155 offset:22528
	ds_read_b128 v[220:223], v155 offset:23552
	global_load_lds_dwordx4 v[208:209], off
	s_add_i32 m0, s40, 0x2000
	s_add_u32 s40, s44, 0x20000
	v_lshl_add_u64 v[224:225], s[44:45], 0, v[136:137]
	s_addc_u32 s41, s45, 0
	s_add_i32 s60, s71, s62
	global_load_lds_dwordx4 v[224:225], off
	v_lshl_add_u64 v[226:227], s[40:41], 0, v[132:133]
	s_mov_b32 m0, s60
	v_lshl_add_u64 v[228:229], s[46:47], 0, v[134:135]
	global_load_lds_dwordx4 v[226:227], off
	v_lshl_add_u64 v[226:227], s[40:41], 0, v[136:137]
	s_add_i32 m0, s60, 0x2000
	s_nop 0
	global_load_lds_dwordx4 v[226:227], off
	v_lshl_add_u64 v[226:227], s[46:47], 0, v[130:131]
	s_mov_b32 m0, s29
	s_nop 0
	global_load_lds_dwordx4 v[226:227], off
	s_mov_b32 m0, s63
	s_nop 0
	global_load_lds_dwordx4 v[228:229], off
	s_waitcnt vmcnt(8)
	s_waitcnt lgkmcnt(0)
	s_barrier
	s_waitcnt lgkmcnt(0)
	v_mfma_f32_16x16x32_bf16 v[62:65], v[156:159], v[188:191], v[62:65]
	v_mfma_f32_16x16x32_bf16 v[58:61], v[164:167], v[188:191], v[58:61]
	v_mfma_f32_16x16x32_bf16 v[50:53], v[164:167], v[196:199], v[50:53]
	v_mfma_f32_16x16x32_bf16 v[54:57], v[156:159], v[196:199], v[54:57]
	v_mfma_f32_16x16x32_bf16 v[38:41], v[156:159], v[204:207], v[38:41]
	v_mfma_f32_16x16x32_bf16 v[34:37], v[164:167], v[204:207], v[34:37]
	v_mfma_f32_16x16x32_bf16 v[18:21], v[164:167], v[216:219], v[18:21]
	v_mfma_f32_16x16x32_bf16 v[22:25], v[156:159], v[216:219], v[22:25]
	v_mfma_f32_16x16x32_bf16 v[62:65], v[160:163], v[192:195], v[62:65]
	v_mfma_f32_16x16x32_bf16 v[58:61], v[168:171], v[192:195], v[58:61]
	v_mfma_f32_16x16x32_bf16 v[50:53], v[168:171], v[200:203], v[50:53]
	v_mfma_f32_16x16x32_bf16 v[54:57], v[160:163], v[200:203], v[54:57]
	v_mfma_f32_16x16x32_bf16 v[38:41], v[160:163], v[212:215], v[38:41]
	v_mfma_f32_16x16x32_bf16 v[34:37], v[168:171], v[212:215], v[34:37]
	v_mfma_f32_16x16x32_bf16 v[18:21], v[168:171], v[220:223], v[18:21]
	v_mfma_f32_16x16x32_bf16 v[22:25], v[160:163], v[220:223], v[22:25]
	v_mfma_f32_16x16x32_bf16 v[46:49], v[172:175], v[188:191], v[46:49]
	v_mfma_f32_16x16x32_bf16 v[42:45], v[180:183], v[188:191], v[42:45]
	v_mfma_f32_16x16x32_bf16 v[26:29], v[180:183], v[196:199], v[26:29]
	v_mfma_f32_16x16x32_bf16 v[30:33], v[172:175], v[196:199], v[30:33]
	v_mfma_f32_16x16x32_bf16 v[14:17], v[172:175], v[204:207], v[14:17]
	v_mfma_f32_16x16x32_bf16 v[10:13], v[180:183], v[204:207], v[10:13]
	v_mfma_f32_16x16x32_bf16 v[2:5], v[180:183], v[216:219], v[2:5]
	v_mfma_f32_16x16x32_bf16 v[6:9], v[172:175], v[216:219], v[6:9]
	v_mfma_f32_16x16x32_bf16 v[46:49], v[176:179], v[192:195], v[46:49]
	v_mfma_f32_16x16x32_bf16 v[42:45], v[184:187], v[192:195], v[42:45]
	v_mfma_f32_16x16x32_bf16 v[26:29], v[184:187], v[200:203], v[26:29]
	v_mfma_f32_16x16x32_bf16 v[30:33], v[176:179], v[200:203], v[30:33]
	v_mfma_f32_16x16x32_bf16 v[14:17], v[176:179], v[212:215], v[14:17]
	v_mfma_f32_16x16x32_bf16 v[10:13], v[184:187], v[212:215], v[10:13]
	v_mfma_f32_16x16x32_bf16 v[2:5], v[184:187], v[220:223], v[2:5]
	v_mfma_f32_16x16x32_bf16 v[6:9], v[176:179], v[220:223], v[6:9]
	s_barrier
	s_add_i32 s60, 0, 0x18000
	s_add_i32 s61, 0, 0x1c000
	v_add_u32_e32 v168, s60, v151
	v_add_u32_e32 v184, s61, v151
	ds_read_b128 v[156:159], v168
	ds_read_b128 v[160:163], v168 offset:1024
	ds_read_b128 v[164:167], v168 offset:2048
	ds_read_b128 v[168:171], v168 offset:3072
	ds_read_b128 v[172:175], v184
	ds_read_b128 v[176:179], v184 offset:1024
	ds_read_b128 v[180:183], v184 offset:2048
	ds_read_b128 v[184:187], v184 offset:3072
	s_add_u32 s40, s46, 0x80000
	s_addc_u32 s41, s47, 0
	s_mov_b32 m0, s64
	v_lshl_add_u64 v[230:231], s[40:41], 0, v[130:131]
	ds_read_b128 v[188:191], v155 offset:32768
	ds_read_b128 v[192:195], v155 offset:33792
	ds_read_b128 v[196:199], v155 offset:34816
	ds_read_b128 v[200:203], v155 offset:35840
	ds_read_b128 v[204:207], v155 offset:36864
	ds_read_b128 v[212:215], v155 offset:37888
	ds_read_b128 v[216:219], v155 offset:38912
	ds_read_b128 v[220:223], v155 offset:39936
	global_load_lds_dwordx4 v[230:231], off
	v_lshl_add_u64 v[230:231], s[40:41], 0, v[134:135]
	s_mov_b32 m0, s65
	s_nop 0
	global_load_lds_dwordx4 v[230:231], off
	s_waitcnt vmcnt(8)
	s_waitcnt lgkmcnt(0)
	s_barrier
	s_waitcnt lgkmcnt(0)
	v_mfma_f32_16x16x32_bf16 v[126:129], v[156:159], v[188:191], v[126:129]
	v_mfma_f32_16x16x32_bf16 v[122:125], v[164:167], v[188:191], v[122:125]
	v_mfma_f32_16x16x32_bf16 v[114:117], v[164:167], v[196:199], v[114:117]
	v_mfma_f32_16x16x32_bf16 v[118:121], v[156:159], v[196:199], v[118:121]
	v_mfma_f32_16x16x32_bf16 v[102:105], v[156:159], v[204:207], v[102:105]
	v_mfma_f32_16x16x32_bf16 v[98:101], v[164:167], v[204:207], v[98:101]
	v_mfma_f32_16x16x32_bf16 v[82:85], v[164:167], v[216:219], v[82:85]
	v_mfma_f32_16x16x32_bf16 v[86:89], v[156:159], v[216:219], v[86:89]
	v_mfma_f32_16x16x32_bf16 v[126:129], v[160:163], v[192:195], v[126:129]
	v_mfma_f32_16x16x32_bf16 v[122:125], v[168:171], v[192:195], v[122:125]
	v_mfma_f32_16x16x32_bf16 v[114:117], v[168:171], v[200:203], v[114:117]
	v_mfma_f32_16x16x32_bf16 v[118:121], v[160:163], v[200:203], v[118:121]
	v_mfma_f32_16x16x32_bf16 v[102:105], v[160:163], v[212:215], v[102:105]
	v_mfma_f32_16x16x32_bf16 v[98:101], v[168:171], v[212:215], v[98:101]
	v_mfma_f32_16x16x32_bf16 v[82:85], v[168:171], v[220:223], v[82:85]
	v_mfma_f32_16x16x32_bf16 v[86:89], v[160:163], v[220:223], v[86:89]
	v_mfma_f32_16x16x32_bf16 v[110:113], v[172:175], v[188:191], v[110:113]
	v_mfma_f32_16x16x32_bf16 v[106:109], v[180:183], v[188:191], v[106:109]
	v_mfma_f32_16x16x32_bf16 v[90:93], v[180:183], v[196:199], v[90:93]
	v_mfma_f32_16x16x32_bf16 v[94:97], v[172:175], v[196:199], v[94:97]
	v_mfma_f32_16x16x32_bf16 v[78:81], v[172:175], v[204:207], v[78:81]
	v_mfma_f32_16x16x32_bf16 v[74:77], v[180:183], v[204:207], v[74:77]
	v_mfma_f32_16x16x32_bf16 v[66:69], v[180:183], v[216:219], v[66:69]
	v_mfma_f32_16x16x32_bf16 v[70:73], v[172:175], v[216:219], v[70:73]
	v_mfma_f32_16x16x32_bf16 v[110:113], v[176:179], v[192:195], v[110:113]
	v_mfma_f32_16x16x32_bf16 v[106:109], v[184:187], v[192:195], v[106:109]
	v_mfma_f32_16x16x32_bf16 v[90:93], v[184:187], v[200:203], v[90:93]
	v_mfma_f32_16x16x32_bf16 v[94:97], v[176:179], v[200:203], v[94:97]
	v_mfma_f32_16x16x32_bf16 v[78:81], v[176:179], v[212:215], v[78:81]
	v_mfma_f32_16x16x32_bf16 v[74:77], v[184:187], v[212:215], v[74:77]
	v_mfma_f32_16x16x32_bf16 v[66:69], v[184:187], v[220:223], v[66:69]
	v_mfma_f32_16x16x32_bf16 v[70:73], v[176:179], v[220:223], v[70:73]
	s_barrier
	s_add_i32 s40, s60, s62
	v_lshl_add_u64 v[208:209], v[208:209], 0, s[10:11]
	s_mov_b32 m0, s40
	ds_read_b128 v[188:191], v155 offset:49152
	ds_read_b128 v[192:195], v155 offset:50176
	ds_read_b128 v[196:199], v155 offset:51200
	ds_read_b128 v[200:203], v155 offset:52224
	ds_read_b128 v[204:207], v155 offset:53248
	ds_read_b128 v[212:215], v155 offset:54272
	ds_read_b128 v[216:219], v155 offset:55296
	ds_read_b128 v[220:223], v155 offset:56320
	global_load_lds_dwordx4 v[208:209], off
	s_add_i32 m0, s40, 0x2000
	s_add_u32 s40, s44, 0x20080
	v_lshl_add_u64 v[208:209], v[224:225], 0, s[10:11]
	s_addc_u32 s41, s45, 0
	s_add_i32 s44, s61, s62
	global_load_lds_dwordx4 v[208:209], off
	v_lshl_add_u64 v[208:209], s[40:41], 0, v[132:133]
	s_mov_b32 m0, s44
	s_nop 0
	global_load_lds_dwordx4 v[208:209], off
	v_lshl_add_u64 v[208:209], s[40:41], 0, v[136:137]
	s_add_i32 m0, s44, 0x2000
	s_nop 0
	global_load_lds_dwordx4 v[208:209], off
	v_lshl_add_u64 v[208:209], v[226:227], 0, s[10:11]
	s_mov_b32 m0, s67
	s_nop 0
	global_load_lds_dwordx4 v[208:209], off
	v_lshl_add_u64 v[208:209], v[228:229], 0, s[10:11]
	s_mov_b32 m0, s68
	s_nop 0
	global_load_lds_dwordx4 v[208:209], off
	s_waitcnt vmcnt(8)
	s_waitcnt lgkmcnt(0)
	s_barrier
	s_waitcnt lgkmcnt(0)
	v_mfma_f32_16x16x32_bf16 v[62:65], v[156:159], v[188:191], v[62:65]
	v_mfma_f32_16x16x32_bf16 v[58:61], v[164:167], v[188:191], v[58:61]
	v_mfma_f32_16x16x32_bf16 v[50:53], v[164:167], v[196:199], v[50:53]
	v_mfma_f32_16x16x32_bf16 v[54:57], v[156:159], v[196:199], v[54:57]
	v_mfma_f32_16x16x32_bf16 v[38:41], v[156:159], v[204:207], v[38:41]
	v_mfma_f32_16x16x32_bf16 v[34:37], v[164:167], v[204:207], v[34:37]
	v_mfma_f32_16x16x32_bf16 v[18:21], v[164:167], v[216:219], v[18:21]
	v_mfma_f32_16x16x32_bf16 v[22:25], v[156:159], v[216:219], v[22:25]
	v_mfma_f32_16x16x32_bf16 v[62:65], v[160:163], v[192:195], v[62:65]
	v_mfma_f32_16x16x32_bf16 v[58:61], v[168:171], v[192:195], v[58:61]
	v_mfma_f32_16x16x32_bf16 v[50:53], v[168:171], v[200:203], v[50:53]
	v_mfma_f32_16x16x32_bf16 v[54:57], v[160:163], v[200:203], v[54:57]
	v_mfma_f32_16x16x32_bf16 v[38:41], v[160:163], v[212:215], v[38:41]
	v_mfma_f32_16x16x32_bf16 v[34:37], v[168:171], v[212:215], v[34:37]
	v_mfma_f32_16x16x32_bf16 v[18:21], v[168:171], v[220:223], v[18:21]
	v_mfma_f32_16x16x32_bf16 v[22:25], v[160:163], v[220:223], v[22:25]
	v_mfma_f32_16x16x32_bf16 v[46:49], v[172:175], v[188:191], v[46:49]
	v_mfma_f32_16x16x32_bf16 v[42:45], v[180:183], v[188:191], v[42:45]
	v_mfma_f32_16x16x32_bf16 v[26:29], v[180:183], v[196:199], v[26:29]
	v_mfma_f32_16x16x32_bf16 v[30:33], v[172:175], v[196:199], v[30:33]
	v_mfma_f32_16x16x32_bf16 v[14:17], v[172:175], v[204:207], v[14:17]
	v_mfma_f32_16x16x32_bf16 v[10:13], v[180:183], v[204:207], v[10:13]
	v_mfma_f32_16x16x32_bf16 v[2:5], v[180:183], v[216:219], v[2:5]
	v_mfma_f32_16x16x32_bf16 v[6:9], v[172:175], v[216:219], v[6:9]
	v_mfma_f32_16x16x32_bf16 v[46:49], v[176:179], v[192:195], v[46:49]
	v_mfma_f32_16x16x32_bf16 v[42:45], v[184:187], v[192:195], v[42:45]
	v_mfma_f32_16x16x32_bf16 v[26:29], v[184:187], v[200:203], v[26:29]
	v_mfma_f32_16x16x32_bf16 v[30:33], v[176:179], v[200:203], v[30:33]
	v_mfma_f32_16x16x32_bf16 v[14:17], v[176:179], v[212:215], v[14:17]
	v_mfma_f32_16x16x32_bf16 v[10:13], v[184:187], v[212:215], v[10:13]
	v_mfma_f32_16x16x32_bf16 v[2:5], v[184:187], v[220:223], v[2:5]
	v_mfma_f32_16x16x32_bf16 v[6:9], v[176:179], v[220:223], v[6:9]
	s_barrier
	s_add_i32 s79, s79, 2
	s_cmp_gt_u32 s79, 5
	s_mov_b64 s[40:41], s[42:43]
	s_cbranch_scc0 .LBB0_911
	s_and_b64 vcc, exec, s[12:13]
	s_cbranch_vccz .LBB0_914
	s_barrier

.LBB0_988:
	ds_read_b128 v[66:69], v215
	ds_read_b128 v[70:73], v215 offset:1024
	ds_read_b128 v[74:77], v215 offset:2048
	ds_read_b128 v[78:81], v215 offset:3072
	ds_read_b128 v[82:85], v216
	ds_read_b128 v[86:89], v216 offset:1024
	ds_read_b128 v[90:93], v216 offset:2048
	ds_read_b128 v[94:97], v216 offset:3072
	s_add_u32 s46, s6, 0xfffc0080
	s_addc_u32 s47, s7, -1
	s_cmp_eq_u32 s81, 12
	s_cselect_b32 s49, s39, s47
	s_cselect_b32 s48, s45, s46
	s_cselect_b32 s47, s37, s80
	s_cselect_b32 s46, s78, s79
	v_lshl_add_u64 v[220:221], s[6:7], 0, v[194:195]
	s_add_i32 m0, s64, 0xc000
	ds_read_b128 v[162:165], v217
	ds_read_b128 v[166:169], v217 offset:1024
	ds_read_b128 v[170:173], v217 offset:2048
	ds_read_b128 v[174:177], v217 offset:3072
	ds_read_b128 v[178:181], v217 offset:4096
	ds_read_b128 v[182:185], v217 offset:5120
	ds_read_b128 v[202:205], v217 offset:6144
	ds_read_b128 v[206:209], v217 offset:7168
	global_load_lds_dwordx4 v[220:221], off
	v_lshl_add_u64 v[220:221], s[6:7], 0, v[196:197]
	s_add_i32 m0, s64, 0xe000
	s_nop 0
	global_load_lds_dwordx4 v[220:221], off
	s_waitcnt vmcnt(8)
	s_waitcnt lgkmcnt(0)
	s_barrier
	s_waitcnt lgkmcnt(0)
	v_mfma_f32_16x16x32_bf16 v[158:161], v[66:69], v[162:165], v[158:161]
	v_mfma_f32_16x16x32_bf16 v[154:157], v[74:77], v[162:165], v[154:157]
	v_mfma_f32_16x16x32_bf16 v[138:141], v[74:77], v[170:173], v[138:141]
	v_mfma_f32_16x16x32_bf16 v[142:145], v[66:69], v[170:173], v[142:145]
	v_mfma_f32_16x16x32_bf16 v[126:129], v[66:69], v[178:181], v[126:129]
	v_mfma_f32_16x16x32_bf16 v[122:125], v[74:77], v[178:181], v[122:125]
	v_mfma_f32_16x16x32_bf16 v[106:109], v[74:77], v[202:205], v[106:109]
	v_mfma_f32_16x16x32_bf16 v[110:113], v[66:69], v[202:205], v[110:113]
	v_mfma_f32_16x16x32_bf16 v[158:161], v[70:73], v[166:169], v[158:161]
	v_mfma_f32_16x16x32_bf16 v[154:157], v[78:81], v[166:169], v[154:157]
	v_mfma_f32_16x16x32_bf16 v[138:141], v[78:81], v[174:177], v[138:141]
	v_mfma_f32_16x16x32_bf16 v[142:145], v[70:73], v[174:177], v[142:145]
	v_mfma_f32_16x16x32_bf16 v[126:129], v[70:73], v[182:185], v[126:129]
	v_mfma_f32_16x16x32_bf16 v[122:125], v[78:81], v[182:185], v[122:125]
	v_mfma_f32_16x16x32_bf16 v[106:109], v[78:81], v[206:209], v[106:109]
	v_mfma_f32_16x16x32_bf16 v[110:113], v[70:73], v[206:209], v[110:113]
	v_mfma_f32_16x16x32_bf16 v[150:153], v[82:85], v[162:165], v[150:153]
	v_mfma_f32_16x16x32_bf16 v[146:149], v[90:93], v[162:165], v[146:149]
	v_mfma_f32_16x16x32_bf16 v[130:133], v[90:93], v[170:173], v[130:133]
	v_mfma_f32_16x16x32_bf16 v[134:137], v[82:85], v[170:173], v[134:137]
	v_mfma_f32_16x16x32_bf16 v[118:121], v[82:85], v[178:181], v[118:121]
	v_mfma_f32_16x16x32_bf16 v[114:117], v[90:93], v[178:181], v[114:117]
	v_mfma_f32_16x16x32_bf16 v[98:101], v[90:93], v[202:205], v[98:101]
	v_mfma_f32_16x16x32_bf16 v[102:105], v[82:85], v[202:205], v[102:105]
	v_mfma_f32_16x16x32_bf16 v[150:153], v[86:89], v[166:169], v[150:153]
	v_mfma_f32_16x16x32_bf16 v[146:149], v[94:97], v[166:169], v[146:149]
	v_mfma_f32_16x16x32_bf16 v[130:133], v[94:97], v[174:177], v[130:133]
	v_mfma_f32_16x16x32_bf16 v[134:137], v[86:89], v[174:177], v[134:137]
	v_mfma_f32_16x16x32_bf16 v[118:121], v[86:89], v[182:185], v[118:121]
	v_mfma_f32_16x16x32_bf16 v[114:117], v[94:97], v[182:185], v[114:117]
	v_mfma_f32_16x16x32_bf16 v[98:101], v[94:97], v[206:209], v[98:101]
	v_mfma_f32_16x16x32_bf16 v[102:105], v[86:89], v[206:209], v[102:105]
	s_barrier
	s_add_i32 s60, s75, s63
	v_lshl_add_u64 v[220:221], s[46:47], 0, v[188:189]
	s_mov_b32 m0, s60
	ds_read_b128 v[162:165], v217 offset:16384
	ds_read_b128 v[166:169], v217 offset:17408
	ds_read_b128 v[170:173], v217 offset:18432
	ds_read_b128 v[174:177], v217 offset:19456
	ds_read_b128 v[178:181], v217 offset:20480
	ds_read_b128 v[182:185], v217 offset:21504
	ds_read_b128 v[202:205], v217 offset:22528
	ds_read_b128 v[206:209], v217 offset:23552
	global_load_lds_dwordx4 v[220:221], off
	s_add_i32 m0, s60, 0x2000
	s_add_u32 s60, s46, 0x40000
	v_lshl_add_u64 v[222:223], s[46:47], 0, v[192:193]
	s_addc_u32 s61, s47, 0
	s_add_i32 s82, s76, s63
	global_load_lds_dwordx4 v[222:223], off
	v_lshl_add_u64 v[224:225], s[60:61], 0, v[188:189]
	s_mov_b32 m0, s82
	v_lshl_add_u64 v[226:227], s[48:49], 0, v[190:191]
	global_load_lds_dwordx4 v[224:225], off
	v_lshl_add_u64 v[224:225], s[60:61], 0, v[192:193]
	s_add_i32 m0, s82, 0x2000
	s_nop 0
	global_load_lds_dwordx4 v[224:225], off
	v_lshl_add_u64 v[224:225], s[48:49], 0, v[186:187]
	s_mov_b32 m0, s64
	s_nop 0
	global_load_lds_dwordx4 v[224:225], off
	s_mov_b32 m0, s65
	s_nop 0
	global_load_lds_dwordx4 v[226:227], off
	s_waitcnt vmcnt(8)
	s_waitcnt lgkmcnt(0)
	s_barrier
	s_waitcnt lgkmcnt(0)
	v_mfma_f32_16x16x32_bf16 v[62:65], v[66:69], v[162:165], v[62:65]
	v_mfma_f32_16x16x32_bf16 v[58:61], v[74:77], v[162:165], v[58:61]
	v_mfma_f32_16x16x32_bf16 v[42:45], v[74:77], v[170:173], v[42:45]
	v_mfma_f32_16x16x32_bf16 v[46:49], v[66:69], v[170:173], v[46:49]
	v_mfma_f32_16x16x32_bf16 v[30:33], v[66:69], v[178:181], v[30:33]
	v_mfma_f32_16x16x32_bf16 v[26:29], v[74:77], v[178:181], v[26:29]
	v_mfma_f32_16x16x32_bf16 v[10:13], v[74:77], v[202:205], v[10:13]
	v_mfma_f32_16x16x32_bf16 v[14:17], v[66:69], v[202:205], v[14:17]
	v_mfma_f32_16x16x32_bf16 v[62:65], v[70:73], v[166:169], v[62:65]
	v_mfma_f32_16x16x32_bf16 v[58:61], v[78:81], v[166:169], v[58:61]
	v_mfma_f32_16x16x32_bf16 v[42:45], v[78:81], v[174:177], v[42:45]
	v_mfma_f32_16x16x32_bf16 v[46:49], v[70:73], v[174:177], v[46:49]
	v_mfma_f32_16x16x32_bf16 v[30:33], v[70:73], v[182:185], v[30:33]
	v_mfma_f32_16x16x32_bf16 v[26:29], v[78:81], v[182:185], v[26:29]
	v_mfma_f32_16x16x32_bf16 v[10:13], v[78:81], v[206:209], v[10:13]
	v_mfma_f32_16x16x32_bf16 v[14:17], v[70:73], v[206:209], v[14:17]
	v_mfma_f32_16x16x32_bf16 v[54:57], v[82:85], v[162:165], v[54:57]
	v_mfma_f32_16x16x32_bf16 v[50:53], v[90:93], v[162:165], v[50:53]
	v_mfma_f32_16x16x32_bf16 v[34:37], v[90:93], v[170:173], v[34:37]
	v_mfma_f32_16x16x32_bf16 v[38:41], v[82:85], v[170:173], v[38:41]
	v_mfma_f32_16x16x32_bf16 v[22:25], v[82:85], v[178:181], v[22:25]
	v_mfma_f32_16x16x32_bf16 v[18:21], v[90:93], v[178:181], v[18:21]
	v_mfma_f32_16x16x32_bf16 v[2:5], v[90:93], v[202:205], v[2:5]
	v_mfma_f32_16x16x32_bf16 v[6:9], v[82:85], v[202:205], v[6:9]
	v_mfma_f32_16x16x32_bf16 v[54:57], v[86:89], v[166:169], v[54:57]
	v_mfma_f32_16x16x32_bf16 v[50:53], v[94:97], v[166:169], v[50:53]
	v_mfma_f32_16x16x32_bf16 v[34:37], v[94:97], v[174:177], v[34:37]
	v_mfma_f32_16x16x32_bf16 v[38:41], v[86:89], v[174:177], v[38:41]
	v_mfma_f32_16x16x32_bf16 v[22:25], v[86:89], v[182:185], v[22:25]
	v_mfma_f32_16x16x32_bf16 v[18:21], v[94:97], v[182:185], v[18:21]
	v_mfma_f32_16x16x32_bf16 v[2:5], v[94:97], v[206:209], v[2:5]
	v_mfma_f32_16x16x32_bf16 v[6:9], v[86:89], v[206:209], v[6:9]
	s_barrier
	s_add_i32 s60, 0, 0x18000
	s_add_i32 s61, 0, 0x1c000
	v_add_u32_e32 v78, s60, v213
	v_add_u32_e32 v94, s61, v213
	ds_read_b128 v[66:69], v78
	ds_read_b128 v[70:73], v78 offset:1024
	ds_read_b128 v[74:77], v78 offset:2048
	ds_read_b128 v[78:81], v78 offset:3072
	ds_read_b128 v[82:85], v94
	ds_read_b128 v[86:89], v94 offset:1024
	ds_read_b128 v[90:93], v94 offset:2048
	ds_read_b128 v[94:97], v94 offset:3072
	s_add_u32 s48, s48, 0x40000
	s_addc_u32 s49, s49, 0
	s_mov_b32 m0, s66
	v_lshl_add_u64 v[228:229], s[48:49], 0, v[186:187]
	ds_read_b128 v[162:165], v217 offset:32768
	ds_read_b128 v[166:169], v217 offset:33792
	ds_read_b128 v[170:173], v217 offset:34816
	ds_read_b128 v[174:177], v217 offset:35840
	ds_read_b128 v[178:181], v217 offset:36864
	ds_read_b128 v[182:185], v217 offset:37888
	ds_read_b128 v[202:205], v217 offset:38912
	ds_read_b128 v[206:209], v217 offset:39936
	global_load_lds_dwordx4 v[228:229], off
	v_lshl_add_u64 v[228:229], s[48:49], 0, v[190:191]
	s_mov_b32 m0, s67
	s_nop 0
	global_load_lds_dwordx4 v[228:229], off
	s_waitcnt vmcnt(8)
	s_waitcnt lgkmcnt(0)
	s_barrier
	s_waitcnt lgkmcnt(0)
	v_mfma_f32_16x16x32_bf16 v[158:161], v[66:69], v[162:165], v[158:161]
	v_mfma_f32_16x16x32_bf16 v[154:157], v[74:77], v[162:165], v[154:157]
	v_mfma_f32_16x16x32_bf16 v[138:141], v[74:77], v[170:173], v[138:141]
	v_mfma_f32_16x16x32_bf16 v[142:145], v[66:69], v[170:173], v[142:145]
	v_mfma_f32_16x16x32_bf16 v[126:129], v[66:69], v[178:181], v[126:129]
	v_mfma_f32_16x16x32_bf16 v[122:125], v[74:77], v[178:181], v[122:125]
	v_mfma_f32_16x16x32_bf16 v[106:109], v[74:77], v[202:205], v[106:109]
	v_mfma_f32_16x16x32_bf16 v[110:113], v[66:69], v[202:205], v[110:113]
	v_mfma_f32_16x16x32_bf16 v[158:161], v[70:73], v[166:169], v[158:161]
	v_mfma_f32_16x16x32_bf16 v[154:157], v[78:81], v[166:169], v[154:157]
	v_mfma_f32_16x16x32_bf16 v[138:141], v[78:81], v[174:177], v[138:141]
	v_mfma_f32_16x16x32_bf16 v[142:145], v[70:73], v[174:177], v[142:145]
	v_mfma_f32_16x16x32_bf16 v[126:129], v[70:73], v[182:185], v[126:129]
	v_mfma_f32_16x16x32_bf16 v[122:125], v[78:81], v[182:185], v[122:125]
	v_mfma_f32_16x16x32_bf16 v[106:109], v[78:81], v[206:209], v[106:109]
	v_mfma_f32_16x16x32_bf16 v[110:113], v[70:73], v[206:209], v[110:113]
	v_mfma_f32_16x16x32_bf16 v[150:153], v[82:85], v[162:165], v[150:153]
	v_mfma_f32_16x16x32_bf16 v[146:149], v[90:93], v[162:165], v[146:149]
	v_mfma_f32_16x16x32_bf16 v[130:133], v[90:93], v[170:173], v[130:133]
	v_mfma_f32_16x16x32_bf16 v[134:137], v[82:85], v[170:173], v[134:137]
	v_mfma_f32_16x16x32_bf16 v[118:121], v[82:85], v[178:181], v[118:121]
	v_mfma_f32_16x16x32_bf16 v[114:117], v[90:93], v[178:181], v[114:117]
	v_mfma_f32_16x16x32_bf16 v[98:101], v[90:93], v[202:205], v[98:101]
	v_mfma_f32_16x16x32_bf16 v[102:105], v[82:85], v[202:205], v[102:105]
	v_mfma_f32_16x16x32_bf16 v[150:153], v[86:89], v[166:169], v[150:153]
	v_mfma_f32_16x16x32_bf16 v[146:149], v[94:97], v[166:169], v[146:149]
	v_mfma_f32_16x16x32_bf16 v[130:133], v[94:97], v[174:177], v[130:133]
	v_mfma_f32_16x16x32_bf16 v[134:137], v[86:89], v[174:177], v[134:137]
	v_mfma_f32_16x16x32_bf16 v[118:121], v[86:89], v[182:185], v[118:121]
	v_mfma_f32_16x16x32_bf16 v[114:117], v[94:97], v[182:185], v[114:117]
	v_mfma_f32_16x16x32_bf16 v[98:101], v[94:97], v[206:209], v[98:101]
	v_mfma_f32_16x16x32_bf16 v[102:105], v[86:89], v[206:209], v[102:105]
	s_barrier
	s_add_i32 s48, s60, s63
	v_lshl_add_u64 v[220:221], v[220:221], 0, s[24:25]
	s_mov_b32 m0, s48
	ds_read_b128 v[162:165], v217 offset:49152
	ds_read_b128 v[166:169], v217 offset:50176
	ds_read_b128 v[170:173], v217 offset:51200
	ds_read_b128 v[174:177], v217 offset:52224
	ds_read_b128 v[178:181], v217 offset:53248
	ds_read_b128 v[182:185], v217 offset:54272
	ds_read_b128 v[202:205], v217 offset:55296
	ds_read_b128 v[206:209], v217 offset:56320
	global_load_lds_dwordx4 v[220:221], off
	s_add_i32 m0, s48, 0x2000
	s_add_u32 s46, s46, 0x40080
	v_lshl_add_u64 v[220:221], v[222:223], 0, s[24:25]
	s_addc_u32 s47, s47, 0
	s_add_i32 s48, s61, s63
	global_load_lds_dwordx4 v[220:221], off
	v_lshl_add_u64 v[220:221], s[46:47], 0, v[188:189]
	s_mov_b32 m0, s48
	s_nop 0
	global_load_lds_dwordx4 v[220:221], off
	v_lshl_add_u64 v[220:221], s[46:47], 0, v[192:193]
	s_add_i32 m0, s48, 0x2000
	s_nop 0
	global_load_lds_dwordx4 v[220:221], off
	v_lshl_add_u64 v[220:221], v[224:225], 0, s[24:25]
	s_mov_b32 m0, s72
	s_nop 0
	global_load_lds_dwordx4 v[220:221], off
	v_lshl_add_u64 v[220:221], v[226:227], 0, s[24:25]
	s_mov_b32 m0, s73
	s_nop 0
	global_load_lds_dwordx4 v[220:221], off
	s_waitcnt vmcnt(8)
	s_waitcnt lgkmcnt(0)
	s_barrier
	s_waitcnt lgkmcnt(0)
	v_mfma_f32_16x16x32_bf16 v[62:65], v[66:69], v[162:165], v[62:65]
	v_mfma_f32_16x16x32_bf16 v[58:61], v[74:77], v[162:165], v[58:61]
	v_mfma_f32_16x16x32_bf16 v[42:45], v[74:77], v[170:173], v[42:45]
	v_mfma_f32_16x16x32_bf16 v[46:49], v[66:69], v[170:173], v[46:49]
	v_mfma_f32_16x16x32_bf16 v[30:33], v[66:69], v[178:181], v[30:33]
	v_mfma_f32_16x16x32_bf16 v[26:29], v[74:77], v[178:181], v[26:29]
	v_mfma_f32_16x16x32_bf16 v[10:13], v[74:77], v[202:205], v[10:13]
	v_mfma_f32_16x16x32_bf16 v[14:17], v[66:69], v[202:205], v[14:17]
	v_mfma_f32_16x16x32_bf16 v[62:65], v[70:73], v[166:169], v[62:65]
	v_mfma_f32_16x16x32_bf16 v[58:61], v[78:81], v[166:169], v[58:61]
	v_mfma_f32_16x16x32_bf16 v[42:45], v[78:81], v[174:177], v[42:45]
	v_mfma_f32_16x16x32_bf16 v[46:49], v[70:73], v[174:177], v[46:49]
	v_mfma_f32_16x16x32_bf16 v[30:33], v[70:73], v[182:185], v[30:33]
	v_mfma_f32_16x16x32_bf16 v[26:29], v[78:81], v[182:185], v[26:29]
	v_mfma_f32_16x16x32_bf16 v[10:13], v[78:81], v[206:209], v[10:13]
	v_mfma_f32_16x16x32_bf16 v[14:17], v[70:73], v[206:209], v[14:17]
	v_mfma_f32_16x16x32_bf16 v[54:57], v[82:85], v[162:165], v[54:57]
	v_mfma_f32_16x16x32_bf16 v[50:53], v[90:93], v[162:165], v[50:53]
	v_mfma_f32_16x16x32_bf16 v[34:37], v[90:93], v[170:173], v[34:37]
	v_mfma_f32_16x16x32_bf16 v[38:41], v[82:85], v[170:173], v[38:41]
	v_mfma_f32_16x16x32_bf16 v[22:25], v[82:85], v[178:181], v[22:25]
	v_mfma_f32_16x16x32_bf16 v[18:21], v[90:93], v[178:181], v[18:21]
	v_mfma_f32_16x16x32_bf16 v[2:5], v[90:93], v[202:205], v[2:5]
	v_mfma_f32_16x16x32_bf16 v[6:9], v[82:85], v[202:205], v[6:9]
	v_mfma_f32_16x16x32_bf16 v[54:57], v[86:89], v[166:169], v[54:57]
	v_mfma_f32_16x16x32_bf16 v[50:53], v[94:97], v[166:169], v[50:53]
	v_mfma_f32_16x16x32_bf16 v[34:37], v[94:97], v[174:177], v[34:37]
	v_mfma_f32_16x16x32_bf16 v[38:41], v[86:89], v[174:177], v[38:41]
	v_mfma_f32_16x16x32_bf16 v[22:25], v[86:89], v[182:185], v[22:25]
	v_mfma_f32_16x16x32_bf16 v[18:21], v[94:97], v[182:185], v[18:21]
	v_mfma_f32_16x16x32_bf16 v[2:5], v[94:97], v[206:209], v[2:5]
	v_mfma_f32_16x16x32_bf16 v[6:9], v[86:89], v[206:209], v[6:9]
	s_barrier
	s_add_i32 s81, s81, 2
	s_add_u32 s6, s6, 0x100
	s_addc_u32 s7, s7, 0
	s_add_u32 s79, s79, 0x100
	s_addc_u32 s80, s80, 0
	s_cmp_gt_u32 s81, 13
	s_cbranch_scc0 .LBB0_988
	s_and_b64 vcc, exec, s[28:29]
	s_cbranch_vccz .LBB0_991
	s_barrier

.LBB0_1087:
	ds_read_b128 v[130:133], v165
	ds_read_b128 v[134:137], v165 offset:1024
	ds_read_b128 v[138:141], v165 offset:2048
	ds_read_b128 v[142:145], v165 offset:3072
	ds_read_b128 v[168:171], v166
	ds_read_b128 v[172:175], v166 offset:1024
	ds_read_b128 v[176:179], v166 offset:2048
	ds_read_b128 v[180:183], v166 offset:3072
	s_add_u32 s28, s26, 0xfffc0080
	s_addc_u32 s29, s27, -1
	s_cmp_eq_u32 s69, 12
	s_cselect_b32 s31, s17, s29
	s_cselect_b32 s30, s65, s28
	s_cselect_b32 s29, s15, s68
	s_cselect_b32 s28, s66, s67
	v_lshl_add_u64 v[216:217], s[26:27], 0, v[154:155]
	s_add_i32 m0, s25, 0xc000
	ds_read_b128 v[184:187], v167
	ds_read_b128 v[188:191], v167 offset:1024
	ds_read_b128 v[192:195], v167 offset:2048
	ds_read_b128 v[196:199], v167 offset:3072
	ds_read_b128 v[200:203], v167 offset:4096
	ds_read_b128 v[204:207], v167 offset:5120
	ds_read_b128 v[208:211], v167 offset:6144
	ds_read_b128 v[212:215], v167 offset:7168
	global_load_lds_dwordx4 v[216:217], off
	v_lshl_add_u64 v[216:217], s[26:27], 0, v[156:157]
	s_add_i32 m0, s25, 0xe000
	s_nop 0
	global_load_lds_dwordx4 v[216:217], off
	s_waitcnt vmcnt(8)
	s_waitcnt lgkmcnt(0)
	s_barrier
	s_waitcnt lgkmcnt(0)
	v_mfma_f32_16x16x32_bf16 v[126:129], v[130:133], v[184:187], v[126:129]
	v_mfma_f32_16x16x32_bf16 v[122:125], v[138:141], v[184:187], v[122:125]
	v_mfma_f32_16x16x32_bf16 v[106:109], v[138:141], v[192:195], v[106:109]
	v_mfma_f32_16x16x32_bf16 v[110:113], v[130:133], v[192:195], v[110:113]
	v_mfma_f32_16x16x32_bf16 v[94:97], v[130:133], v[200:203], v[94:97]
	v_mfma_f32_16x16x32_bf16 v[90:93], v[138:141], v[200:203], v[90:93]
	v_mfma_f32_16x16x32_bf16 v[74:77], v[138:141], v[208:211], v[74:77]
	v_mfma_f32_16x16x32_bf16 v[78:81], v[130:133], v[208:211], v[78:81]
	v_mfma_f32_16x16x32_bf16 v[126:129], v[134:137], v[188:191], v[126:129]
	v_mfma_f32_16x16x32_bf16 v[122:125], v[142:145], v[188:191], v[122:125]
	v_mfma_f32_16x16x32_bf16 v[106:109], v[142:145], v[196:199], v[106:109]
	v_mfma_f32_16x16x32_bf16 v[110:113], v[134:137], v[196:199], v[110:113]
	v_mfma_f32_16x16x32_bf16 v[94:97], v[134:137], v[204:207], v[94:97]
	v_mfma_f32_16x16x32_bf16 v[90:93], v[142:145], v[204:207], v[90:93]
	v_mfma_f32_16x16x32_bf16 v[74:77], v[142:145], v[212:215], v[74:77]
	v_mfma_f32_16x16x32_bf16 v[78:81], v[134:137], v[212:215], v[78:81]
	v_mfma_f32_16x16x32_bf16 v[118:121], v[168:171], v[184:187], v[118:121]
	v_mfma_f32_16x16x32_bf16 v[114:117], v[176:179], v[184:187], v[114:117]
	v_mfma_f32_16x16x32_bf16 v[98:101], v[176:179], v[192:195], v[98:101]
	v_mfma_f32_16x16x32_bf16 v[102:105], v[168:171], v[192:195], v[102:105]
	v_mfma_f32_16x16x32_bf16 v[86:89], v[168:171], v[200:203], v[86:89]
	v_mfma_f32_16x16x32_bf16 v[82:85], v[176:179], v[200:203], v[82:85]
	v_mfma_f32_16x16x32_bf16 v[66:69], v[176:179], v[208:211], v[66:69]
	v_mfma_f32_16x16x32_bf16 v[70:73], v[168:171], v[208:211], v[70:73]
	v_mfma_f32_16x16x32_bf16 v[118:121], v[172:175], v[188:191], v[118:121]
	v_mfma_f32_16x16x32_bf16 v[114:117], v[180:183], v[188:191], v[114:117]
	v_mfma_f32_16x16x32_bf16 v[98:101], v[180:183], v[196:199], v[98:101]
	v_mfma_f32_16x16x32_bf16 v[102:105], v[172:175], v[196:199], v[102:105]
	v_mfma_f32_16x16x32_bf16 v[86:89], v[172:175], v[204:207], v[86:89]
	v_mfma_f32_16x16x32_bf16 v[82:85], v[180:183], v[204:207], v[82:85]
	v_mfma_f32_16x16x32_bf16 v[66:69], v[180:183], v[212:215], v[66:69]
	v_mfma_f32_16x16x32_bf16 v[70:73], v[172:175], v[212:215], v[70:73]
	s_barrier
	s_add_i32 s60, s49, s37
	v_lshl_add_u64 v[216:217], s[28:29], 0, v[150:151]
	s_mov_b32 m0, s60
	ds_read_b128 v[184:187], v167 offset:16384
	ds_read_b128 v[188:191], v167 offset:17408
	ds_read_b128 v[192:195], v167 offset:18432
	ds_read_b128 v[196:199], v167 offset:19456
	ds_read_b128 v[200:203], v167 offset:20480
	ds_read_b128 v[204:207], v167 offset:21504
	ds_read_b128 v[208:211], v167 offset:22528
	ds_read_b128 v[212:215], v167 offset:23552
	global_load_lds_dwordx4 v[216:217], off
	s_add_i32 m0, s60, 0x2000
	s_add_u32 s60, s28, 0x40000
	v_lshl_add_u64 v[218:219], s[28:29], 0, v[146:147]
	s_addc_u32 s61, s29, 0
	s_add_i32 s70, s50, s37
	global_load_lds_dwordx4 v[218:219], off
	v_lshl_add_u64 v[220:221], s[60:61], 0, v[150:151]
	s_mov_b32 m0, s70
	v_lshl_add_u64 v[222:223], s[30:31], 0, v[148:149]
	global_load_lds_dwordx4 v[220:221], off
	v_lshl_add_u64 v[220:221], s[60:61], 0, v[146:147]
	s_add_i32 m0, s70, 0x2000
	s_nop 0
	global_load_lds_dwordx4 v[220:221], off
	v_lshl_add_u64 v[220:221], s[30:31], 0, v[152:153]
	s_mov_b32 m0, s25
	s_nop 0
	global_load_lds_dwordx4 v[220:221], off
	s_mov_b32 m0, s43
	s_nop 0
	global_load_lds_dwordx4 v[222:223], off
	s_waitcnt vmcnt(8)
	s_waitcnt lgkmcnt(0)
	s_barrier
	s_waitcnt lgkmcnt(0)
	v_mfma_f32_16x16x32_bf16 v[62:65], v[130:133], v[184:187], v[62:65]
	v_mfma_f32_16x16x32_bf16 v[58:61], v[138:141], v[184:187], v[58:61]
	v_mfma_f32_16x16x32_bf16 v[42:45], v[138:141], v[192:195], v[42:45]
	v_mfma_f32_16x16x32_bf16 v[46:49], v[130:133], v[192:195], v[46:49]
	v_mfma_f32_16x16x32_bf16 v[30:33], v[130:133], v[200:203], v[30:33]
	v_mfma_f32_16x16x32_bf16 v[26:29], v[138:141], v[200:203], v[26:29]
	v_mfma_f32_16x16x32_bf16 v[10:13], v[138:141], v[208:211], v[10:13]
	v_mfma_f32_16x16x32_bf16 v[14:17], v[130:133], v[208:211], v[14:17]
	v_mfma_f32_16x16x32_bf16 v[62:65], v[134:137], v[188:191], v[62:65]
	v_mfma_f32_16x16x32_bf16 v[58:61], v[142:145], v[188:191], v[58:61]
	v_mfma_f32_16x16x32_bf16 v[42:45], v[142:145], v[196:199], v[42:45]
	v_mfma_f32_16x16x32_bf16 v[46:49], v[134:137], v[196:199], v[46:49]
	v_mfma_f32_16x16x32_bf16 v[30:33], v[134:137], v[204:207], v[30:33]
	v_mfma_f32_16x16x32_bf16 v[26:29], v[142:145], v[204:207], v[26:29]
	v_mfma_f32_16x16x32_bf16 v[10:13], v[142:145], v[212:215], v[10:13]
	v_mfma_f32_16x16x32_bf16 v[14:17], v[134:137], v[212:215], v[14:17]
	v_mfma_f32_16x16x32_bf16 v[54:57], v[168:171], v[184:187], v[54:57]
	v_mfma_f32_16x16x32_bf16 v[50:53], v[176:179], v[184:187], v[50:53]
	v_mfma_f32_16x16x32_bf16 v[34:37], v[176:179], v[192:195], v[34:37]
	v_mfma_f32_16x16x32_bf16 v[38:41], v[168:171], v[192:195], v[38:41]
	v_mfma_f32_16x16x32_bf16 v[22:25], v[168:171], v[200:203], v[22:25]
	v_mfma_f32_16x16x32_bf16 v[18:21], v[176:179], v[200:203], v[18:21]
	v_mfma_f32_16x16x32_bf16 v[2:5], v[176:179], v[208:211], v[2:5]
	v_mfma_f32_16x16x32_bf16 v[6:9], v[168:171], v[208:211], v[6:9]
	v_mfma_f32_16x16x32_bf16 v[54:57], v[172:175], v[188:191], v[54:57]
	v_mfma_f32_16x16x32_bf16 v[50:53], v[180:183], v[188:191], v[50:53]
	v_mfma_f32_16x16x32_bf16 v[34:37], v[180:183], v[196:199], v[34:37]
	v_mfma_f32_16x16x32_bf16 v[38:41], v[172:175], v[196:199], v[38:41]
	v_mfma_f32_16x16x32_bf16 v[22:25], v[172:175], v[204:207], v[22:25]
	v_mfma_f32_16x16x32_bf16 v[18:21], v[180:183], v[204:207], v[18:21]
	v_mfma_f32_16x16x32_bf16 v[2:5], v[180:183], v[212:215], v[2:5]
	v_mfma_f32_16x16x32_bf16 v[6:9], v[172:175], v[212:215], v[6:9]
	s_barrier
	s_add_i32 s60, 0, 0x18000
	s_add_i32 s61, 0, 0x1c000
	v_add_u32_e32 v142, s60, v163
	v_add_u32_e32 v180, s61, v163
	ds_read_b128 v[130:133], v142
	ds_read_b128 v[134:137], v142 offset:1024
	ds_read_b128 v[138:141], v142 offset:2048
	ds_read_b128 v[142:145], v142 offset:3072
	ds_read_b128 v[168:171], v180
	ds_read_b128 v[172:175], v180 offset:1024
	ds_read_b128 v[176:179], v180 offset:2048
	ds_read_b128 v[180:183], v180 offset:3072
	s_add_u32 s30, s30, 0x40000
	s_addc_u32 s31, s31, 0
	s_mov_b32 m0, s44
	v_lshl_add_u64 v[224:225], s[30:31], 0, v[152:153]
	ds_read_b128 v[184:187], v167 offset:32768
	ds_read_b128 v[188:191], v167 offset:33792
	ds_read_b128 v[192:195], v167 offset:34816
	ds_read_b128 v[196:199], v167 offset:35840
	ds_read_b128 v[200:203], v167 offset:36864
	ds_read_b128 v[204:207], v167 offset:37888
	ds_read_b128 v[208:211], v167 offset:38912
	ds_read_b128 v[212:215], v167 offset:39936
	global_load_lds_dwordx4 v[224:225], off
	v_lshl_add_u64 v[224:225], s[30:31], 0, v[148:149]
	s_mov_b32 m0, s45
	s_nop 0
	global_load_lds_dwordx4 v[224:225], off
	s_waitcnt vmcnt(8)
	s_waitcnt lgkmcnt(0)
	s_barrier
	s_waitcnt lgkmcnt(0)
	v_mfma_f32_16x16x32_bf16 v[126:129], v[130:133], v[184:187], v[126:129]
	v_mfma_f32_16x16x32_bf16 v[122:125], v[138:141], v[184:187], v[122:125]
	v_mfma_f32_16x16x32_bf16 v[106:109], v[138:141], v[192:195], v[106:109]
	v_mfma_f32_16x16x32_bf16 v[110:113], v[130:133], v[192:195], v[110:113]
	v_mfma_f32_16x16x32_bf16 v[94:97], v[130:133], v[200:203], v[94:97]
	v_mfma_f32_16x16x32_bf16 v[90:93], v[138:141], v[200:203], v[90:93]
	v_mfma_f32_16x16x32_bf16 v[74:77], v[138:141], v[208:211], v[74:77]
	v_mfma_f32_16x16x32_bf16 v[78:81], v[130:133], v[208:211], v[78:81]
	v_mfma_f32_16x16x32_bf16 v[126:129], v[134:137], v[188:191], v[126:129]
	v_mfma_f32_16x16x32_bf16 v[122:125], v[142:145], v[188:191], v[122:125]
	v_mfma_f32_16x16x32_bf16 v[106:109], v[142:145], v[196:199], v[106:109]
	v_mfma_f32_16x16x32_bf16 v[110:113], v[134:137], v[196:199], v[110:113]
	v_mfma_f32_16x16x32_bf16 v[94:97], v[134:137], v[204:207], v[94:97]
	v_mfma_f32_16x16x32_bf16 v[90:93], v[142:145], v[204:207], v[90:93]
	v_mfma_f32_16x16x32_bf16 v[74:77], v[142:145], v[212:215], v[74:77]
	v_mfma_f32_16x16x32_bf16 v[78:81], v[134:137], v[212:215], v[78:81]
	v_mfma_f32_16x16x32_bf16 v[118:121], v[168:171], v[184:187], v[118:121]
	v_mfma_f32_16x16x32_bf16 v[114:117], v[176:179], v[184:187], v[114:117]
	v_mfma_f32_16x16x32_bf16 v[98:101], v[176:179], v[192:195], v[98:101]
	v_mfma_f32_16x16x32_bf16 v[102:105], v[168:171], v[192:195], v[102:105]
	v_mfma_f32_16x16x32_bf16 v[86:89], v[168:171], v[200:203], v[86:89]
	v_mfma_f32_16x16x32_bf16 v[82:85], v[176:179], v[200:203], v[82:85]
	v_mfma_f32_16x16x32_bf16 v[66:69], v[176:179], v[208:211], v[66:69]
	v_mfma_f32_16x16x32_bf16 v[70:73], v[168:171], v[208:211], v[70:73]
	v_mfma_f32_16x16x32_bf16 v[118:121], v[172:175], v[188:191], v[118:121]
	v_mfma_f32_16x16x32_bf16 v[114:117], v[180:183], v[188:191], v[114:117]
	v_mfma_f32_16x16x32_bf16 v[98:101], v[180:183], v[196:199], v[98:101]
	v_mfma_f32_16x16x32_bf16 v[102:105], v[172:175], v[196:199], v[102:105]
	v_mfma_f32_16x16x32_bf16 v[86:89], v[172:175], v[204:207], v[86:89]
	v_mfma_f32_16x16x32_bf16 v[82:85], v[180:183], v[204:207], v[82:85]
	v_mfma_f32_16x16x32_bf16 v[66:69], v[180:183], v[212:215], v[66:69]
	v_mfma_f32_16x16x32_bf16 v[70:73], v[172:175], v[212:215], v[70:73]
	s_barrier
	s_add_i32 s30, s60, s37
	v_lshl_add_u64 v[216:217], v[216:217], 0, s[10:11]
	s_mov_b32 m0, s30
	ds_read_b128 v[184:187], v167 offset:49152
	ds_read_b128 v[188:191], v167 offset:50176
	ds_read_b128 v[192:195], v167 offset:51200
	ds_read_b128 v[196:199], v167 offset:52224
	ds_read_b128 v[200:203], v167 offset:53248
	ds_read_b128 v[204:207], v167 offset:54272
	ds_read_b128 v[208:211], v167 offset:55296
	ds_read_b128 v[212:215], v167 offset:56320
	global_load_lds_dwordx4 v[216:217], off
	s_add_i32 m0, s30, 0x2000
	s_add_u32 s28, s28, 0x40080
	v_lshl_add_u64 v[216:217], v[218:219], 0, s[10:11]
	s_addc_u32 s29, s29, 0
	s_add_i32 s30, s61, s37
	global_load_lds_dwordx4 v[216:217], off
	v_lshl_add_u64 v[216:217], s[28:29], 0, v[150:151]
	s_mov_b32 m0, s30
	s_nop 0
	global_load_lds_dwordx4 v[216:217], off
	v_lshl_add_u64 v[216:217], s[28:29], 0, v[146:147]
	s_add_i32 m0, s30, 0x2000
	s_nop 0
	global_load_lds_dwordx4 v[216:217], off
	v_lshl_add_u64 v[216:217], v[220:221], 0, s[10:11]
	s_mov_b32 m0, s47
	s_nop 0
	global_load_lds_dwordx4 v[216:217], off
	v_lshl_add_u64 v[216:217], v[222:223], 0, s[10:11]
	s_mov_b32 m0, s48
	s_nop 0
	global_load_lds_dwordx4 v[216:217], off
	s_waitcnt vmcnt(8)
	s_waitcnt lgkmcnt(0)
	s_barrier
	s_waitcnt lgkmcnt(0)
	v_mfma_f32_16x16x32_bf16 v[62:65], v[130:133], v[184:187], v[62:65]
	v_mfma_f32_16x16x32_bf16 v[58:61], v[138:141], v[184:187], v[58:61]
	v_mfma_f32_16x16x32_bf16 v[42:45], v[138:141], v[192:195], v[42:45]
	v_mfma_f32_16x16x32_bf16 v[46:49], v[130:133], v[192:195], v[46:49]
	v_mfma_f32_16x16x32_bf16 v[30:33], v[130:133], v[200:203], v[30:33]
	v_mfma_f32_16x16x32_bf16 v[26:29], v[138:141], v[200:203], v[26:29]
	v_mfma_f32_16x16x32_bf16 v[10:13], v[138:141], v[208:211], v[10:13]
	v_mfma_f32_16x16x32_bf16 v[14:17], v[130:133], v[208:211], v[14:17]
	v_mfma_f32_16x16x32_bf16 v[62:65], v[134:137], v[188:191], v[62:65]
	v_mfma_f32_16x16x32_bf16 v[58:61], v[142:145], v[188:191], v[58:61]
	v_mfma_f32_16x16x32_bf16 v[42:45], v[142:145], v[196:199], v[42:45]
	v_mfma_f32_16x16x32_bf16 v[46:49], v[134:137], v[196:199], v[46:49]
	v_mfma_f32_16x16x32_bf16 v[30:33], v[134:137], v[204:207], v[30:33]
	v_mfma_f32_16x16x32_bf16 v[26:29], v[142:145], v[204:207], v[26:29]
	v_mfma_f32_16x16x32_bf16 v[10:13], v[142:145], v[212:215], v[10:13]
	v_mfma_f32_16x16x32_bf16 v[14:17], v[134:137], v[212:215], v[14:17]
	v_mfma_f32_16x16x32_bf16 v[54:57], v[168:171], v[184:187], v[54:57]
	v_mfma_f32_16x16x32_bf16 v[50:53], v[176:179], v[184:187], v[50:53]
	v_mfma_f32_16x16x32_bf16 v[34:37], v[176:179], v[192:195], v[34:37]
	v_mfma_f32_16x16x32_bf16 v[38:41], v[168:171], v[192:195], v[38:41]
	v_mfma_f32_16x16x32_bf16 v[22:25], v[168:171], v[200:203], v[22:25]
	v_mfma_f32_16x16x32_bf16 v[18:21], v[176:179], v[200:203], v[18:21]
	v_mfma_f32_16x16x32_bf16 v[2:5], v[176:179], v[208:211], v[2:5]
	v_mfma_f32_16x16x32_bf16 v[6:9], v[168:171], v[208:211], v[6:9]
	v_mfma_f32_16x16x32_bf16 v[54:57], v[172:175], v[188:191], v[54:57]
	v_mfma_f32_16x16x32_bf16 v[50:53], v[180:183], v[188:191], v[50:53]
	v_mfma_f32_16x16x32_bf16 v[34:37], v[180:183], v[196:199], v[34:37]
	v_mfma_f32_16x16x32_bf16 v[38:41], v[172:175], v[196:199], v[38:41]
	v_mfma_f32_16x16x32_bf16 v[22:25], v[172:175], v[204:207], v[22:25]
	v_mfma_f32_16x16x32_bf16 v[18:21], v[180:183], v[204:207], v[18:21]
	v_mfma_f32_16x16x32_bf16 v[2:5], v[180:183], v[212:215], v[2:5]
	v_mfma_f32_16x16x32_bf16 v[6:9], v[172:175], v[212:215], v[6:9]
	s_barrier
	s_add_i32 s69, s69, 2
	s_add_u32 s26, s26, 0x100
	s_addc_u32 s27, s27, 0
	s_add_u32 s67, s67, 0x100
	s_addc_u32 s68, s68, 0
	s_cmp_gt_u32 s69, 13
	s_cbranch_scc0 .LBB0_1087
	s_and_b64 vcc, exec, s[12:13]
	s_cbranch_vccz .LBB0_1090
	s_barrier

.LBB0_1168:
	ds_read_b128 v[104:107], v201
	ds_read_b128 v[108:111], v201 offset:1024
	ds_read_b128 v[116:119], v201 offset:2048
	ds_read_b128 v[124:127], v201 offset:3072
	ds_read_b128 v[162:165], v202
	ds_read_b128 v[166:169], v202 offset:1024
	ds_read_b128 v[170:173], v202 offset:2048
	ds_read_b128 v[174:177], v202 offset:3072
	s_add_u32 s28, s26, 0xfff50080
	s_addc_u32 s29, s27, -1
	s_cmp_eq_u32 s59, 40
	s_cselect_b32 s31, s11, s29
	s_cselect_b32 s30, s10, s28
	s_cselect_b32 s29, s19, s25
	s_cselect_b32 s28, s18, s23
	v_lshl_add_u64 v[244:245], s[26:27], 0, v[154:155]
	s_add_i32 m0, s38, 0xc000
	ds_read_b128 v[178:181], v203
	ds_read_b128 v[216:219], v203 offset:1024
	ds_read_b128 v[220:223], v203 offset:2048
	ds_read_b128 v[224:227], v203 offset:3072
	ds_read_b128 v[228:231], v203 offset:4096
	ds_read_b128 v[232:235], v203 offset:5120
	ds_read_b128 v[236:239], v203 offset:6144
	ds_read_b128 v[240:243], v203 offset:7168
	global_load_lds_dwordx4 v[244:245], off
	v_lshl_add_u64 v[244:245], s[26:27], 0, v[156:157]
	s_add_i32 m0, s38, 0xe000
	s_nop 0
	global_load_lds_dwordx4 v[244:245], off
	s_waitcnt vmcnt(8)
	s_waitcnt lgkmcnt(0)
	s_barrier
	s_waitcnt lgkmcnt(0)
	v_mfma_f32_16x16x32_bf16 v[140:143], v[104:107], v[178:181], v[140:143]
	v_mfma_f32_16x16x32_bf16 v[136:139], v[116:119], v[178:181], v[136:139]
	v_mfma_f32_16x16x32_bf16 v[112:115], v[116:119], v[220:223], v[112:115]
	v_mfma_f32_16x16x32_bf16 v[120:123], v[104:107], v[220:223], v[120:123]
	v_mfma_f32_16x16x32_bf16 v[92:95], v[104:107], v[228:231], v[92:95]
	v_mfma_f32_16x16x32_bf16 v[88:91], v[116:119], v[228:231], v[88:91]
	v_mfma_f32_16x16x32_bf16 v[72:75], v[116:119], v[236:239], v[72:75]
	v_mfma_f32_16x16x32_bf16 v[76:79], v[104:107], v[236:239], v[76:79]
	v_mfma_f32_16x16x32_bf16 v[140:143], v[108:111], v[216:219], v[140:143]
	v_mfma_f32_16x16x32_bf16 v[136:139], v[124:127], v[216:219], v[136:139]
	v_mfma_f32_16x16x32_bf16 v[112:115], v[124:127], v[224:227], v[112:115]
	v_mfma_f32_16x16x32_bf16 v[120:123], v[108:111], v[224:227], v[120:123]
	v_mfma_f32_16x16x32_bf16 v[92:95], v[108:111], v[232:235], v[92:95]
	v_mfma_f32_16x16x32_bf16 v[88:91], v[124:127], v[232:235], v[88:91]
	v_mfma_f32_16x16x32_bf16 v[72:75], v[124:127], v[240:243], v[72:75]
	v_mfma_f32_16x16x32_bf16 v[76:79], v[108:111], v[240:243], v[76:79]
	v_mfma_f32_16x16x32_bf16 v[132:135], v[162:165], v[178:181], v[132:135]
	v_mfma_f32_16x16x32_bf16 v[128:131], v[170:173], v[178:181], v[128:131]
	v_mfma_f32_16x16x32_bf16 v[96:99], v[170:173], v[220:223], v[96:99]
	v_mfma_f32_16x16x32_bf16 v[100:103], v[162:165], v[220:223], v[100:103]
	v_mfma_f32_16x16x32_bf16 v[84:87], v[162:165], v[228:231], v[84:87]
	v_mfma_f32_16x16x32_bf16 v[80:83], v[170:173], v[228:231], v[80:83]
	v_mfma_f32_16x16x32_bf16 v[64:67], v[170:173], v[236:239], v[64:67]
	v_mfma_f32_16x16x32_bf16 v[68:71], v[162:165], v[236:239], v[68:71]
	v_mfma_f32_16x16x32_bf16 v[132:135], v[166:169], v[216:219], v[132:135]
	v_mfma_f32_16x16x32_bf16 v[128:131], v[174:177], v[216:219], v[128:131]
	v_mfma_f32_16x16x32_bf16 v[96:99], v[174:177], v[224:227], v[96:99]
	v_mfma_f32_16x16x32_bf16 v[100:103], v[166:169], v[224:227], v[100:103]
	v_mfma_f32_16x16x32_bf16 v[84:87], v[166:169], v[232:235], v[84:87]
	v_mfma_f32_16x16x32_bf16 v[80:83], v[174:177], v[232:235], v[80:83]
	v_mfma_f32_16x16x32_bf16 v[64:67], v[174:177], v[240:243], v[64:67]
	v_mfma_f32_16x16x32_bf16 v[68:71], v[166:169], v[240:243], v[68:71]
	s_barrier
	s_add_i32 s60, s51, s37
	v_lshl_add_u64 v[244:245], s[28:29], 0, v[146:147]
	s_mov_b32 m0, s60
	ds_read_b128 v[178:181], v203 offset:16384
	ds_read_b128 v[216:219], v203 offset:17408
	ds_read_b128 v[220:223], v203 offset:18432
	ds_read_b128 v[224:227], v203 offset:19456
	ds_read_b128 v[228:231], v203 offset:20480
	ds_read_b128 v[232:235], v203 offset:21504
	ds_read_b128 v[236:239], v203 offset:22528
	ds_read_b128 v[240:243], v203 offset:23552
	global_load_lds_dwordx4 v[244:245], off
	s_add_i32 m0, s60, 0x2000
	s_add_u32 s60, s28, 0xb0000
	v_lshl_add_u64 v[246:247], s[28:29], 0, v[150:151]
	s_addc_u32 s61, s29, 0
	s_add_i32 s62, s56, s37
	global_load_lds_dwordx4 v[246:247], off
	v_lshl_add_u64 v[248:249], s[60:61], 0, v[146:147]
	s_mov_b32 m0, s62
	v_lshl_add_u64 v[250:251], s[30:31], 0, v[148:149]
	global_load_lds_dwordx4 v[248:249], off
	v_lshl_add_u64 v[248:249], s[60:61], 0, v[150:151]
	s_add_i32 m0, s62, 0x2000
	s_nop 0
	global_load_lds_dwordx4 v[248:249], off
	v_lshl_add_u64 v[248:249], s[30:31], 0, v[144:145]
	s_mov_b32 m0, s38
	s_nop 0
	global_load_lds_dwordx4 v[248:249], off
	s_mov_b32 m0, s39
	s_nop 0
	global_load_lds_dwordx4 v[250:251], off
	s_waitcnt vmcnt(8)
	s_waitcnt lgkmcnt(0)
	s_barrier
	s_waitcnt lgkmcnt(0)
	v_mfma_f32_16x16x32_bf16 v[60:63], v[104:107], v[178:181], v[60:63]
	v_mfma_f32_16x16x32_bf16 v[56:59], v[116:119], v[178:181], v[56:59]
	v_mfma_f32_16x16x32_bf16 v[40:43], v[116:119], v[220:223], v[40:43]
	v_mfma_f32_16x16x32_bf16 v[44:47], v[104:107], v[220:223], v[44:47]
	v_mfma_f32_16x16x32_bf16 v[28:31], v[104:107], v[228:231], v[28:31]
	v_mfma_f32_16x16x32_bf16 v[24:27], v[116:119], v[228:231], v[24:27]
	v_mfma_f32_16x16x32_bf16 v[8:11], v[116:119], v[236:239], v[8:11]
	v_mfma_f32_16x16x32_bf16 v[12:15], v[104:107], v[236:239], v[12:15]
	v_mfma_f32_16x16x32_bf16 v[60:63], v[108:111], v[216:219], v[60:63]
	v_mfma_f32_16x16x32_bf16 v[56:59], v[124:127], v[216:219], v[56:59]
	v_mfma_f32_16x16x32_bf16 v[40:43], v[124:127], v[224:227], v[40:43]
	v_mfma_f32_16x16x32_bf16 v[44:47], v[108:111], v[224:227], v[44:47]
	v_mfma_f32_16x16x32_bf16 v[28:31], v[108:111], v[232:235], v[28:31]
	v_mfma_f32_16x16x32_bf16 v[24:27], v[124:127], v[232:235], v[24:27]
	v_mfma_f32_16x16x32_bf16 v[8:11], v[124:127], v[240:243], v[8:11]
	v_mfma_f32_16x16x32_bf16 v[12:15], v[108:111], v[240:243], v[12:15]
	v_mfma_f32_16x16x32_bf16 v[52:55], v[162:165], v[178:181], v[52:55]
	v_mfma_f32_16x16x32_bf16 v[48:51], v[170:173], v[178:181], v[48:51]
	v_mfma_f32_16x16x32_bf16 v[32:35], v[170:173], v[220:223], v[32:35]
	v_mfma_f32_16x16x32_bf16 v[36:39], v[162:165], v[220:223], v[36:39]
	v_mfma_f32_16x16x32_bf16 v[20:23], v[162:165], v[228:231], v[20:23]
	v_mfma_f32_16x16x32_bf16 v[16:19], v[170:173], v[228:231], v[16:19]
	v_mfma_f32_16x16x32_bf16 v[0:3], v[170:173], v[236:239], v[0:3]
	v_mfma_f32_16x16x32_bf16 v[4:7], v[162:165], v[236:239], v[4:7]
	v_mfma_f32_16x16x32_bf16 v[52:55], v[166:169], v[216:219], v[52:55]
	v_mfma_f32_16x16x32_bf16 v[48:51], v[174:177], v[216:219], v[48:51]
	v_mfma_f32_16x16x32_bf16 v[32:35], v[174:177], v[224:227], v[32:35]
	v_mfma_f32_16x16x32_bf16 v[36:39], v[166:169], v[224:227], v[36:39]
	v_mfma_f32_16x16x32_bf16 v[20:23], v[166:169], v[232:235], v[20:23]
	v_mfma_f32_16x16x32_bf16 v[16:19], v[174:177], v[232:235], v[16:19]
	v_mfma_f32_16x16x32_bf16 v[0:3], v[174:177], v[240:243], v[0:3]
	v_mfma_f32_16x16x32_bf16 v[4:7], v[166:169], v[240:243], v[4:7]
	s_barrier
	s_add_i32 s60, 0, 0x18000
	s_add_i32 s61, 0, 0x1c000
	v_add_u32_e32 v124, s60, v183
	v_add_u32_e32 v174, s61, v183
	ds_read_b128 v[104:107], v124
	ds_read_b128 v[108:111], v124 offset:1024
	ds_read_b128 v[116:119], v124 offset:2048
	ds_read_b128 v[124:127], v124 offset:3072
	ds_read_b128 v[162:165], v174
	ds_read_b128 v[166:169], v174 offset:1024
	ds_read_b128 v[170:173], v174 offset:2048
	ds_read_b128 v[174:177], v174 offset:3072
	s_add_u32 s30, s30, 0xb0000
	s_addc_u32 s31, s31, 0
	s_mov_b32 m0, s40
	v_lshl_add_u64 v[252:253], s[30:31], 0, v[144:145]
	ds_read_b128 v[178:181], v203 offset:32768
	ds_read_b128 v[216:219], v203 offset:33792
	ds_read_b128 v[220:223], v203 offset:34816
	ds_read_b128 v[224:227], v203 offset:35840
	ds_read_b128 v[228:231], v203 offset:36864
	ds_read_b128 v[232:235], v203 offset:37888
	ds_read_b128 v[236:239], v203 offset:38912
	ds_read_b128 v[240:243], v203 offset:39936
	global_load_lds_dwordx4 v[252:253], off
	v_lshl_add_u64 v[252:253], s[30:31], 0, v[148:149]
	s_mov_b32 m0, s41
	s_nop 0
	global_load_lds_dwordx4 v[252:253], off
	s_waitcnt vmcnt(8)
	s_waitcnt lgkmcnt(0)
	s_barrier
	s_waitcnt lgkmcnt(0)
	v_mfma_f32_16x16x32_bf16 v[140:143], v[104:107], v[178:181], v[140:143]
	v_mfma_f32_16x16x32_bf16 v[136:139], v[116:119], v[178:181], v[136:139]
	v_mfma_f32_16x16x32_bf16 v[112:115], v[116:119], v[220:223], v[112:115]
	v_mfma_f32_16x16x32_bf16 v[120:123], v[104:107], v[220:223], v[120:123]
	v_mfma_f32_16x16x32_bf16 v[92:95], v[104:107], v[228:231], v[92:95]
	v_mfma_f32_16x16x32_bf16 v[88:91], v[116:119], v[228:231], v[88:91]
	v_mfma_f32_16x16x32_bf16 v[72:75], v[116:119], v[236:239], v[72:75]
	v_mfma_f32_16x16x32_bf16 v[76:79], v[104:107], v[236:239], v[76:79]
	v_mfma_f32_16x16x32_bf16 v[140:143], v[108:111], v[216:219], v[140:143]
	v_mfma_f32_16x16x32_bf16 v[136:139], v[124:127], v[216:219], v[136:139]
	v_mfma_f32_16x16x32_bf16 v[112:115], v[124:127], v[224:227], v[112:115]
	v_mfma_f32_16x16x32_bf16 v[120:123], v[108:111], v[224:227], v[120:123]
	v_mfma_f32_16x16x32_bf16 v[92:95], v[108:111], v[232:235], v[92:95]
	v_mfma_f32_16x16x32_bf16 v[88:91], v[124:127], v[232:235], v[88:91]
	v_mfma_f32_16x16x32_bf16 v[72:75], v[124:127], v[240:243], v[72:75]
	v_mfma_f32_16x16x32_bf16 v[76:79], v[108:111], v[240:243], v[76:79]
	v_mfma_f32_16x16x32_bf16 v[132:135], v[162:165], v[178:181], v[132:135]
	v_mfma_f32_16x16x32_bf16 v[128:131], v[170:173], v[178:181], v[128:131]
	v_mfma_f32_16x16x32_bf16 v[96:99], v[170:173], v[220:223], v[96:99]
	v_mfma_f32_16x16x32_bf16 v[100:103], v[162:165], v[220:223], v[100:103]
	v_mfma_f32_16x16x32_bf16 v[84:87], v[162:165], v[228:231], v[84:87]
	v_mfma_f32_16x16x32_bf16 v[80:83], v[170:173], v[228:231], v[80:83]
	v_mfma_f32_16x16x32_bf16 v[64:67], v[170:173], v[236:239], v[64:67]
	v_mfma_f32_16x16x32_bf16 v[68:71], v[162:165], v[236:239], v[68:71]
	v_mfma_f32_16x16x32_bf16 v[132:135], v[166:169], v[216:219], v[132:135]
	v_mfma_f32_16x16x32_bf16 v[128:131], v[174:177], v[216:219], v[128:131]
	v_mfma_f32_16x16x32_bf16 v[96:99], v[174:177], v[224:227], v[96:99]
	v_mfma_f32_16x16x32_bf16 v[100:103], v[166:169], v[224:227], v[100:103]
	v_mfma_f32_16x16x32_bf16 v[84:87], v[166:169], v[232:235], v[84:87]
	v_mfma_f32_16x16x32_bf16 v[80:83], v[174:177], v[232:235], v[80:83]
	v_mfma_f32_16x16x32_bf16 v[64:67], v[174:177], v[240:243], v[64:67]
	v_mfma_f32_16x16x32_bf16 v[68:71], v[166:169], v[240:243], v[68:71]
	s_barrier
	s_add_i32 s30, s60, s37
	v_lshl_add_u64 v[244:245], v[244:245], 0, s[14:15]
	s_mov_b32 m0, s30
	ds_read_b128 v[178:181], v203 offset:49152
	ds_read_b128 v[216:219], v203 offset:50176
	ds_read_b128 v[220:223], v203 offset:51200
	ds_read_b128 v[224:227], v203 offset:52224
	ds_read_b128 v[228:231], v203 offset:53248
	ds_read_b128 v[232:235], v203 offset:54272
	ds_read_b128 v[236:239], v203 offset:55296
	ds_read_b128 v[240:243], v203 offset:56320
	global_load_lds_dwordx4 v[244:245], off
	s_add_i32 m0, s30, 0x2000
	s_add_u32 s28, s28, 0xb0080
	v_lshl_add_u64 v[244:245], v[246:247], 0, s[14:15]
	s_addc_u32 s29, s29, 0
	s_add_i32 s30, s61, s37
	global_load_lds_dwordx4 v[244:245], off
	v_lshl_add_u64 v[244:245], s[28:29], 0, v[146:147]
	s_mov_b32 m0, s30
	s_nop 0
	global_load_lds_dwordx4 v[244:245], off
	v_lshl_add_u64 v[244:245], s[28:29], 0, v[150:151]
	s_add_i32 m0, s30, 0x2000
	s_nop 0
	global_load_lds_dwordx4 v[244:245], off
	v_lshl_add_u64 v[244:245], v[248:249], 0, s[14:15]
	s_mov_b32 m0, s48
	s_nop 0
	global_load_lds_dwordx4 v[244:245], off
	v_lshl_add_u64 v[244:245], v[250:251], 0, s[14:15]
	s_mov_b32 m0, s49
	s_nop 0
	global_load_lds_dwordx4 v[244:245], off
	s_waitcnt vmcnt(8)
	s_waitcnt lgkmcnt(0)
	s_barrier
	s_waitcnt lgkmcnt(0)
	v_mfma_f32_16x16x32_bf16 v[60:63], v[104:107], v[178:181], v[60:63]
	v_mfma_f32_16x16x32_bf16 v[56:59], v[116:119], v[178:181], v[56:59]
	v_mfma_f32_16x16x32_bf16 v[40:43], v[116:119], v[220:223], v[40:43]
	v_mfma_f32_16x16x32_bf16 v[44:47], v[104:107], v[220:223], v[44:47]
	v_mfma_f32_16x16x32_bf16 v[28:31], v[104:107], v[228:231], v[28:31]
	v_mfma_f32_16x16x32_bf16 v[24:27], v[116:119], v[228:231], v[24:27]
	v_mfma_f32_16x16x32_bf16 v[8:11], v[116:119], v[236:239], v[8:11]
	v_mfma_f32_16x16x32_bf16 v[12:15], v[104:107], v[236:239], v[12:15]
	v_mfma_f32_16x16x32_bf16 v[60:63], v[108:111], v[216:219], v[60:63]
	v_mfma_f32_16x16x32_bf16 v[56:59], v[124:127], v[216:219], v[56:59]
	v_mfma_f32_16x16x32_bf16 v[40:43], v[124:127], v[224:227], v[40:43]
	v_mfma_f32_16x16x32_bf16 v[44:47], v[108:111], v[224:227], v[44:47]
	v_mfma_f32_16x16x32_bf16 v[28:31], v[108:111], v[232:235], v[28:31]
	v_mfma_f32_16x16x32_bf16 v[24:27], v[124:127], v[232:235], v[24:27]
	v_mfma_f32_16x16x32_bf16 v[8:11], v[124:127], v[240:243], v[8:11]
	v_mfma_f32_16x16x32_bf16 v[12:15], v[108:111], v[240:243], v[12:15]
	v_mfma_f32_16x16x32_bf16 v[52:55], v[162:165], v[178:181], v[52:55]
	v_mfma_f32_16x16x32_bf16 v[48:51], v[170:173], v[178:181], v[48:51]
	v_mfma_f32_16x16x32_bf16 v[32:35], v[170:173], v[220:223], v[32:35]
	v_mfma_f32_16x16x32_bf16 v[36:39], v[162:165], v[220:223], v[36:39]
	v_mfma_f32_16x16x32_bf16 v[20:23], v[162:165], v[228:231], v[20:23]
	v_mfma_f32_16x16x32_bf16 v[16:19], v[170:173], v[228:231], v[16:19]
	v_mfma_f32_16x16x32_bf16 v[0:3], v[170:173], v[236:239], v[0:3]
	v_mfma_f32_16x16x32_bf16 v[4:7], v[162:165], v[236:239], v[4:7]
	v_mfma_f32_16x16x32_bf16 v[52:55], v[166:169], v[216:219], v[52:55]
	v_mfma_f32_16x16x32_bf16 v[48:51], v[174:177], v[216:219], v[48:51]
	v_mfma_f32_16x16x32_bf16 v[32:35], v[174:177], v[224:227], v[32:35]
	v_mfma_f32_16x16x32_bf16 v[36:39], v[166:169], v[224:227], v[36:39]
	v_mfma_f32_16x16x32_bf16 v[20:23], v[166:169], v[232:235], v[20:23]
	v_mfma_f32_16x16x32_bf16 v[16:19], v[174:177], v[232:235], v[16:19]
	v_mfma_f32_16x16x32_bf16 v[0:3], v[174:177], v[240:243], v[0:3]
	v_mfma_f32_16x16x32_bf16 v[4:7], v[166:169], v[240:243], v[4:7]
	s_barrier
	s_add_i32 s59, s59, 2
	s_add_u32 s26, s26, 0x100
	s_addc_u32 s27, s27, 0
	s_add_u32 s23, s23, 0x100
	s_addc_u32 s25, s25, 0
	s_cmp_gt_u32 s59, 41
	s_cbranch_scc0 .LBB0_1168
	s_and_b64 vcc, exec, s[16:17]
	s_cbranch_vccz .LBB0_1171
	s_barrier
